# v18 + select descent loop: one packed reduction chain per round, scalar bit counter, hand-written loop for all 8 key-count classes
# baseline (speedup 1.0000x reference)
; #define DPP_ADDI(ctrl, rmask) v += __builtin_amdgcn_update_dpp(0, v, ctrl, rmask, 0xF, false)
; __device__ __forceinline__ int wave_sum_i_dpp(int v) {
;     ...
;     DPP_ADDI(0xB1, 0xF); DPP_ADDI(0x4E, 0xF); DPP_ADDI(0x141, 0xF); DPP_ADDI(0x140, 0xF); DPP_ADDI(0x142, 0xA); DPP_ADDI(0x143, 0xC);
;     ...
;     return __builtin_amdgcn_readlane(v, 63);
; }
; __device__ __forceinline__ void select_item(const Frame& F, int l, int samp, int b, int c, int qg) {
;     ...
;             const unsigned candA = prefixA | (1u << bit), candB = prefixB | (1u << bit), cA1 = candA - 1u, cB1 = candB - 1u; unsigned a4[4] = {0u, 0u, 0u, 0u}, b4[4] = {0u, 0u, 0u, 0u};
; #pragma unroll
;             for (int j = 0; j < 64; ++j) { a4[j & 3] += min(__builtin_elementwise_sub_sat(keyA[j], cA1), 1u); b4[j & 3] += min(__builtin_elementwise_sub_sat(keyB[j], cB1), 1u); }
;             const int cntA = wave_sum_i_dpp((int)((a4[0] + a4[1]) + (a4[2] + a4[3]))), cntB = wave_sum_i_dpp((int)((b4[0] + b4[1]) + (b4[2] + b4[3])));
;             if (!doneA) { if (cntA >= 256) prefixA = candA; if (cntA == 256) doneA = true; }
;             if (!doneB) { if (cntB >= 256) prefixB = candB; if (cntB == 256) doneB = true; }
;         }
.Lsel_m1:
	s_mov_b64 s[6:7], s[0:1]
	s_lshl_b32 s0, 1, s11
	s_or_b32 s13, s0, s10
	s_or_b32 s12, s0, s33
	s_add_i32 s14, s13, -1
	s_add_i32 s15, s12, -1
	s_cmp_eq_u32 s11, 0
	s_cselect_b64 s[8:9], -1, 0
	s_add_i32 s11, s11, -1
	s_mov_b64 s[4:5], s[42:43]
	s_cmp_lt_u32 s14, 0x7fffff
	s_cselect_b32 s0, 56, 0
	v_mov_b32_e32 v2, s0
	s_cmp_lt_u32 s15, 0x7fffff
	s_cselect_b32 s0, 56, 0
	v_mov_b32_e32 v3, s0
	v_cmp_lt_u32_e64 s[0:1], s14, v127
	v_cmp_lt_u32_e64 s[100:101], s15, v81
	v_cmp_lt_u32_e32 vcc, s14, v4
	v_cndmask_b32_e64 v132, 0, 1, s[0:1]
	v_cndmask_b32_e64 v133, 0, 1, s[100:101]
	v_addc_co_u32_e32 v2, vcc, v2, v132, vcc
	v_cmp_lt_u32_e32 vcc, s15, v6
	v_cmp_lt_u32_e64 s[0:1], s14, v65
	v_cmp_lt_u32_e64 s[100:101], s15, v7
	v_addc_co_u32_e32 v3, vcc, v3, v133, vcc
	v_cmp_lt_u32_e32 vcc, s14, v129
	v_cndmask_b32_e64 v132, 0, 1, s[0:1]
	v_cndmask_b32_e64 v133, 0, 1, s[100:101]
	v_addc_co_u32_e32 v2, vcc, v2, v132, vcc
	v_cmp_lt_u32_e32 vcc, s15, v8
	v_cmp_lt_u32_e64 s[0:1], s14, v67
	v_cmp_lt_u32_e64 s[100:101], s15, v83
	v_addc_co_u32_e32 v3, vcc, v3, v133, vcc
	v_cmp_lt_u32_e32 vcc, s14, v128
	v_cndmask_b32_e64 v132, 0, 1, s[0:1]
	v_cndmask_b32_e64 v133, 0, 1, s[100:101]
	v_addc_co_u32_e32 v2, vcc, v2, v132, vcc
	v_cmp_lt_u32_e32 vcc, s15, v82
	v_cmp_lt_u32_e64 s[0:1], s14, v131
	v_cmp_lt_u32_e64 s[100:101], s15, v85
	v_addc_co_u32_e32 v3, vcc, v3, v133, vcc
	v_cmp_lt_u32_e32 vcc, s14, v130
	v_cndmask_b32_e64 v132, 0, 1, s[0:1]
	v_cndmask_b32_e64 v133, 0, 1, s[100:101]
	v_addc_co_u32_e32 v2, vcc, v2, v132, vcc
	v_cmp_lt_u32_e32 vcc, s15, v84
	s_nop 1
	v_addc_co_u32_e32 v3, vcc, v3, v133, vcc
	v_lshl_add_u32 v2, v3, 16, v2
	s_nop 1
	v_add_u32_dpp v2, v2, v2 quad_perm:[1,0,3,2] row_mask:0xf bank_mask:0xf bound_ctrl:1
	s_nop 1
	v_add_u32_dpp v2, v2, v2 quad_perm:[2,3,0,1] row_mask:0xf bank_mask:0xf bound_ctrl:1
	s_nop 1
	v_add_u32_dpp v2, v2, v2 row_half_mirror row_mask:0xf bank_mask:0xf bound_ctrl:1
	s_nop 1
	v_add_u32_dpp v2, v2, v2 row_mirror row_mask:0xf bank_mask:0xf bound_ctrl:1
	s_nop 1
	v_add_u32_dpp v2, v2, v2 row_bcast:15 row_mask:0xa bank_mask:0xf
	s_nop 1
	v_add_u32_dpp v2, v2, v2 row_bcast:31 row_mask:0xc bank_mask:0xf
	s_nop 0
	v_readlane_b32 s0, v2, 63
	s_lshr_b32 s14, s0, 16
	s_and_b32 s0, s0, 0xffff
	s_cmpk_gt_i32 s0, 0xff
	s_cselect_b32 s13, s13, s10
	s_cmpk_eq_i32 s0, 0x100
	s_cselect_b64 s[0:1], -1, 0
	s_or_b64 s[0:1], s[6:7], s[0:1]
	s_and_b64 s[6:7], s[6:7], exec
	s_cselect_b32 s10, s10, s13
	s_cmpk_gt_i32 s14, 0xff
	s_cselect_b32 s12, s12, s33
	s_cmpk_eq_i32 s14, 0x100
	s_cselect_b64 s[6:7], -1, 0
	s_or_b64 s[42:43], s[42:43], s[6:7]
	s_and_b64 s[4:5], s[4:5], exec
	s_cselect_b32 s33, s33, s12
	s_and_b64 s[4:5], s[0:1], s[42:43]
	s_or_b64 s[4:5], s[8:9], s[4:5]
	s_and_b64 vcc, exec, s[4:5]
	s_cbranch_vccz .Lsel_m1
	s_branch .Lsel_exit
.Lsel_m2:
	s_mov_b64 s[6:7], s[0:1]
	s_lshl_b32 s0, 1, s11
	s_or_b32 s13, s0, s10
	s_or_b32 s12, s0, s33
	s_add_i32 s14, s13, -1
	s_add_i32 s15, s12, -1
	s_cmp_eq_u32 s11, 0
	s_cselect_b64 s[8:9], -1, 0
	s_add_i32 s11, s11, -1
	s_mov_b64 s[4:5], s[42:43]
	s_cmp_lt_u32 s14, 0x7fffff
	s_cselect_b32 s0, 48, 0
	v_mov_b32_e32 v2, s0
	s_cmp_lt_u32 s15, 0x7fffff
	s_cselect_b32 s0, 48, 0
	v_mov_b32_e32 v3, s0
	v_cmp_lt_u32_e64 s[0:1], s14, v127
	v_cmp_lt_u32_e64 s[100:101], s15, v81
	v_cmp_lt_u32_e32 vcc, s14, v4
	v_cndmask_b32_e64 v132, 0, 1, s[0:1]
	v_cndmask_b32_e64 v133, 0, 1, s[100:101]
	v_addc_co_u32_e32 v2, vcc, v2, v132, vcc
	v_cmp_lt_u32_e32 vcc, s15, v6
	v_cmp_lt_u32_e64 s[0:1], s14, v65
	v_cmp_lt_u32_e64 s[100:101], s15, v7
	v_addc_co_u32_e32 v3, vcc, v3, v133, vcc
	v_cmp_lt_u32_e32 vcc, s14, v129
	v_cndmask_b32_e64 v132, 0, 1, s[0:1]
	v_cndmask_b32_e64 v133, 0, 1, s[100:101]
	v_addc_co_u32_e32 v2, vcc, v2, v132, vcc
	v_cmp_lt_u32_e32 vcc, s15, v8
	v_cmp_lt_u32_e64 s[0:1], s14, v70
	v_cmp_lt_u32_e64 s[100:101], s15, v9
	v_addc_co_u32_e32 v3, vcc, v3, v133, vcc
	v_cmp_lt_u32_e32 vcc, s14, v67
	v_cndmask_b32_e64 v132, 0, 1, s[0:1]
	v_cndmask_b32_e64 v133, 0, 1, s[100:101]
	v_addc_co_u32_e32 v2, vcc, v2, v132, vcc
	v_cmp_lt_u32_e32 vcc, s15, v10
	v_cmp_lt_u32_e64 s[0:1], s14, v5
	v_cmp_lt_u32_e64 s[100:101], s15, v11
	v_addc_co_u32_e32 v3, vcc, v3, v133, vcc
	v_cmp_lt_u32_e32 vcc, s14, v69
	v_cndmask_b32_e64 v132, 0, 1, s[0:1]
	v_cndmask_b32_e64 v133, 0, 1, s[100:101]
	v_addc_co_u32_e32 v2, vcc, v2, v132, vcc
	v_cmp_lt_u32_e32 vcc, s15, v12
	v_cmp_lt_u32_e64 s[0:1], s14, v66
	v_cmp_lt_u32_e64 s[100:101], s15, v83
	v_addc_co_u32_e32 v3, vcc, v3, v133, vcc
	v_cmp_lt_u32_e32 vcc, s14, v71
	v_cndmask_b32_e64 v132, 0, 1, s[0:1]
	v_cndmask_b32_e64 v133, 0, 1, s[100:101]
	v_addc_co_u32_e32 v2, vcc, v2, v132, vcc
	v_cmp_lt_u32_e32 vcc, s15, v15
	v_cmp_lt_u32_e64 s[0:1], s14, v128
	v_cmp_lt_u32_e64 s[100:101], s15, v82
	v_addc_co_u32_e32 v3, vcc, v3, v133, vcc
	v_cmp_lt_u32_e32 vcc, s14, v75
	v_cndmask_b32_e64 v132, 0, 1, s[0:1]
	v_cndmask_b32_e64 v133, 0, 1, s[100:101]
	v_addc_co_u32_e32 v2, vcc, v2, v132, vcc
	v_cmp_lt_u32_e32 vcc, s15, v16
	v_cmp_lt_u32_e64 s[0:1], s14, v131
	v_cmp_lt_u32_e64 s[100:101], s15, v85
	v_addc_co_u32_e32 v3, vcc, v3, v133, vcc
	v_cmp_lt_u32_e32 vcc, s14, v68
	v_cndmask_b32_e64 v132, 0, 1, s[0:1]
	v_cndmask_b32_e64 v133, 0, 1, s[100:101]
	v_addc_co_u32_e32 v2, vcc, v2, v132, vcc
	v_cmp_lt_u32_e32 vcc, s15, v13
	v_cmp_lt_u32_e64 s[0:1], s14, v130
	v_cmp_lt_u32_e64 s[100:101], s15, v84
	v_addc_co_u32_e32 v3, vcc, v3, v133, vcc
	v_cmp_lt_u32_e32 vcc, s14, v73
	v_cndmask_b32_e64 v132, 0, 1, s[0:1]
	v_cndmask_b32_e64 v133, 0, 1, s[100:101]
	v_addc_co_u32_e32 v2, vcc, v2, v132, vcc
	v_cmp_lt_u32_e32 vcc, s15, v14
	s_nop 1
	v_addc_co_u32_e32 v3, vcc, v3, v133, vcc
	v_lshl_add_u32 v2, v3, 16, v2
	s_nop 1
	v_add_u32_dpp v2, v2, v2 quad_perm:[1,0,3,2] row_mask:0xf bank_mask:0xf bound_ctrl:1
	s_nop 1
	v_add_u32_dpp v2, v2, v2 quad_perm:[2,3,0,1] row_mask:0xf bank_mask:0xf bound_ctrl:1
	s_nop 1
	v_add_u32_dpp v2, v2, v2 row_half_mirror row_mask:0xf bank_mask:0xf bound_ctrl:1
	s_nop 1
	v_add_u32_dpp v2, v2, v2 row_mirror row_mask:0xf bank_mask:0xf bound_ctrl:1
	s_nop 1
	v_add_u32_dpp v2, v2, v2 row_bcast:15 row_mask:0xa bank_mask:0xf
	s_nop 1
	v_add_u32_dpp v2, v2, v2 row_bcast:31 row_mask:0xc bank_mask:0xf
	s_nop 0
	v_readlane_b32 s0, v2, 63
	s_lshr_b32 s14, s0, 16
	s_and_b32 s0, s0, 0xffff
	s_cmpk_gt_i32 s0, 0xff
	s_cselect_b32 s13, s13, s10
	s_cmpk_eq_i32 s0, 0x100
	s_cselect_b64 s[0:1], -1, 0
	s_or_b64 s[0:1], s[6:7], s[0:1]
	s_and_b64 s[6:7], s[6:7], exec
	s_cselect_b32 s10, s10, s13
	s_cmpk_gt_i32 s14, 0xff
	s_cselect_b32 s12, s12, s33
	s_cmpk_eq_i32 s14, 0x100
	s_cselect_b64 s[6:7], -1, 0
	s_or_b64 s[42:43], s[42:43], s[6:7]
	s_and_b64 s[4:5], s[4:5], exec
	s_cselect_b32 s33, s33, s12
	s_and_b64 s[4:5], s[0:1], s[42:43]
	s_or_b64 s[4:5], s[8:9], s[4:5]
	s_and_b64 vcc, exec, s[4:5]
	s_cbranch_vccz .Lsel_m2
	s_branch .Lsel_exit
; #define DPP_ADDI(ctrl, rmask) v += __builtin_amdgcn_update_dpp(0, v, ctrl, rmask, 0xF, false)
; __device__ __forceinline__ int wave_sum_i_dpp(int v) {
;     ...
;     DPP_ADDI(0xB1, 0xF); DPP_ADDI(0x4E, 0xF); DPP_ADDI(0x141, 0xF); DPP_ADDI(0x140, 0xF); DPP_ADDI(0x142, 0xA); DPP_ADDI(0x143, 0xC);
;     ...
;     return __builtin_amdgcn_readlane(v, 63);
; }
; __device__ __forceinline__ void select_item(const Frame& F, int l, int samp, int b, int c, int qg) {
;     ...
;             const unsigned candA = prefixA | (1u << bit), candB = prefixB | (1u << bit), cA1 = candA - 1u, cB1 = candB - 1u; unsigned a4[4] = {0u, 0u, 0u, 0u}, b4[4] = {0u, 0u, 0u, 0u};
; #pragma unroll
;             for (int j = 0; j < 64; ++j) { a4[j & 3] += min(__builtin_elementwise_sub_sat(keyA[j], cA1), 1u); b4[j & 3] += min(__builtin_elementwise_sub_sat(keyB[j], cB1), 1u); }
;             const int cntA = wave_sum_i_dpp((int)((a4[0] + a4[1]) + (a4[2] + a4[3]))), cntB = wave_sum_i_dpp((int)((b4[0] + b4[1]) + (b4[2] + b4[3])));
;             if (!doneA) { if (cntA >= 256) prefixA = candA; if (cntA == 256) doneA = true; }
;             if (!doneB) { if (cntB >= 256) prefixB = candB; if (cntB == 256) doneB = true; }
;         }
.Lsel_m3:
	s_mov_b64 s[6:7], s[0:1]
	s_lshl_b32 s0, 1, s11
	s_or_b32 s13, s0, s10
	s_or_b32 s12, s0, s33
	s_add_i32 s14, s13, -1
	s_add_i32 s15, s12, -1
	s_cmp_eq_u32 s11, 0
	s_cselect_b64 s[8:9], -1, 0
	s_add_i32 s11, s11, -1
	s_mov_b64 s[4:5], s[42:43]
	s_cmp_lt_u32 s14, 0x7fffff
	s_cselect_b32 s0, 40, 0
	v_mov_b32_e32 v2, s0
	s_cmp_lt_u32 s15, 0x7fffff
	s_cselect_b32 s0, 40, 0
	v_mov_b32_e32 v3, s0
	v_cmp_lt_u32_e64 s[0:1], s14, v127
	v_cmp_lt_u32_e64 s[100:101], s15, v81
	v_cmp_lt_u32_e32 vcc, s14, v4
	v_cndmask_b32_e64 v132, 0, 1, s[0:1]
	v_cndmask_b32_e64 v133, 0, 1, s[100:101]
	v_addc_co_u32_e32 v2, vcc, v2, v132, vcc
	v_cmp_lt_u32_e32 vcc, s15, v6
	v_cmp_lt_u32_e64 s[0:1], s14, v65
	v_cmp_lt_u32_e64 s[100:101], s15, v7
	v_addc_co_u32_e32 v3, vcc, v3, v133, vcc
	v_cmp_lt_u32_e32 vcc, s14, v129
	v_cndmask_b32_e64 v132, 0, 1, s[0:1]
	v_cndmask_b32_e64 v133, 0, 1, s[100:101]
	v_addc_co_u32_e32 v2, vcc, v2, v132, vcc
	v_cmp_lt_u32_e32 vcc, s15, v8
	v_cmp_lt_u32_e64 s[0:1], s14, v70
	v_cmp_lt_u32_e64 s[100:101], s15, v9
	v_addc_co_u32_e32 v3, vcc, v3, v133, vcc
	v_cmp_lt_u32_e32 vcc, s14, v67
	v_cndmask_b32_e64 v132, 0, 1, s[0:1]
	v_cndmask_b32_e64 v133, 0, 1, s[100:101]
	v_addc_co_u32_e32 v2, vcc, v2, v132, vcc
	v_cmp_lt_u32_e32 vcc, s15, v10
	v_cmp_lt_u32_e64 s[0:1], s14, v5
	v_cmp_lt_u32_e64 s[100:101], s15, v11
	v_addc_co_u32_e32 v3, vcc, v3, v133, vcc
	v_cmp_lt_u32_e32 vcc, s14, v69
	v_cndmask_b32_e64 v132, 0, 1, s[0:1]
	v_cndmask_b32_e64 v133, 0, 1, s[100:101]
	v_addc_co_u32_e32 v2, vcc, v2, v132, vcc
	v_cmp_lt_u32_e32 vcc, s15, v12
	v_cmp_lt_u32_e64 s[0:1], s14, v66
	v_cmp_lt_u32_e64 s[100:101], s15, v17
	v_addc_co_u32_e32 v3, vcc, v3, v133, vcc
	v_cmp_lt_u32_e32 vcc, s14, v71
	v_cndmask_b32_e64 v132, 0, 1, s[0:1]
	v_cndmask_b32_e64 v133, 0, 1, s[100:101]
	v_addc_co_u32_e32 v2, vcc, v2, v132, vcc
	v_cmp_lt_u32_e32 vcc, s15, v18
	v_cmp_lt_u32_e64 s[0:1], s14, v79
	v_cmp_lt_u32_e64 s[100:101], s15, v19
	v_addc_co_u32_e32 v3, vcc, v3, v133, vcc
	v_cmp_lt_u32_e32 vcc, s14, v72
	v_cndmask_b32_e64 v132, 0, 1, s[0:1]
	v_cndmask_b32_e64 v133, 0, 1, s[100:101]
	v_addc_co_u32_e32 v2, vcc, v2, v132, vcc
	v_cmp_lt_u32_e32 vcc, s15, v20
	v_cmp_lt_u32_e64 s[0:1], s14, v76
	v_cmp_lt_u32_e64 s[100:101], s15, v83
	v_addc_co_u32_e32 v3, vcc, v3, v133, vcc
	v_cmp_lt_u32_e32 vcc, s14, v74
	v_cndmask_b32_e64 v132, 0, 1, s[0:1]
	v_cndmask_b32_e64 v133, 0, 1, s[100:101]
	v_addc_co_u32_e32 v2, vcc, v2, v132, vcc
	v_cmp_lt_u32_e32 vcc, s15, v15
	v_cmp_lt_u32_e64 s[0:1], s14, v78
	v_cmp_lt_u32_e64 s[100:101], s15, v23
	v_addc_co_u32_e32 v3, vcc, v3, v133, vcc
	v_cmp_lt_u32_e32 vcc, s14, v128
	v_cndmask_b32_e64 v132, 0, 1, s[0:1]
	v_cndmask_b32_e64 v133, 0, 1, s[100:101]
	v_addc_co_u32_e32 v2, vcc, v2, v132, vcc
	v_cmp_lt_u32_e32 vcc, s15, v82
	v_cmp_lt_u32_e64 s[0:1], s14, v75
	v_cmp_lt_u32_e64 s[100:101], s15, v16
	v_addc_co_u32_e32 v3, vcc, v3, v133, vcc
	v_cmp_lt_u32_e32 vcc, s14, v87
	v_cndmask_b32_e64 v132, 0, 1, s[0:1]
	v_cndmask_b32_e64 v133, 0, 1, s[100:101]
	v_addc_co_u32_e32 v2, vcc, v2, v132, vcc
	v_cmp_lt_u32_e32 vcc, s15, v24
	v_cmp_lt_u32_e64 s[0:1], s14, v131
	v_cmp_lt_u32_e64 s[100:101], s15, v85
	v_addc_co_u32_e32 v3, vcc, v3, v133, vcc
	v_cmp_lt_u32_e32 vcc, s14, v68
	v_cndmask_b32_e64 v132, 0, 1, s[0:1]
	v_cndmask_b32_e64 v133, 0, 1, s[100:101]
	v_addc_co_u32_e32 v2, vcc, v2, v132, vcc
	v_cmp_lt_u32_e32 vcc, s15, v13
	v_cmp_lt_u32_e64 s[0:1], s14, v77
	v_cmp_lt_u32_e64 s[100:101], s15, v21
	v_addc_co_u32_e32 v3, vcc, v3, v133, vcc
	v_cmp_lt_u32_e32 vcc, s14, v130
	v_cndmask_b32_e64 v132, 0, 1, s[0:1]
	v_cndmask_b32_e64 v133, 0, 1, s[100:101]
	v_addc_co_u32_e32 v2, vcc, v2, v132, vcc
	v_cmp_lt_u32_e32 vcc, s15, v84
	v_cmp_lt_u32_e64 s[0:1], s14, v73
	v_cmp_lt_u32_e64 s[100:101], s15, v14
	v_addc_co_u32_e32 v3, vcc, v3, v133, vcc
	v_cmp_lt_u32_e32 vcc, s14, v80
	v_cndmask_b32_e64 v132, 0, 1, s[0:1]
	v_cndmask_b32_e64 v133, 0, 1, s[100:101]
	v_addc_co_u32_e32 v2, vcc, v2, v132, vcc
	v_cmp_lt_u32_e32 vcc, s15, v22
	s_nop 1
	v_addc_co_u32_e32 v3, vcc, v3, v133, vcc
	v_lshl_add_u32 v2, v3, 16, v2
	s_nop 1
	v_add_u32_dpp v2, v2, v2 quad_perm:[1,0,3,2] row_mask:0xf bank_mask:0xf bound_ctrl:1
	s_nop 1
	v_add_u32_dpp v2, v2, v2 quad_perm:[2,3,0,1] row_mask:0xf bank_mask:0xf bound_ctrl:1
	s_nop 1
	v_add_u32_dpp v2, v2, v2 row_half_mirror row_mask:0xf bank_mask:0xf bound_ctrl:1
	s_nop 1
	v_add_u32_dpp v2, v2, v2 row_mirror row_mask:0xf bank_mask:0xf bound_ctrl:1
	s_nop 1
	v_add_u32_dpp v2, v2, v2 row_bcast:15 row_mask:0xa bank_mask:0xf
	s_nop 1
	v_add_u32_dpp v2, v2, v2 row_bcast:31 row_mask:0xc bank_mask:0xf
	s_nop 0
	v_readlane_b32 s0, v2, 63
	s_lshr_b32 s14, s0, 16
	s_and_b32 s0, s0, 0xffff
	s_cmpk_gt_i32 s0, 0xff
	s_cselect_b32 s13, s13, s10
	s_cmpk_eq_i32 s0, 0x100
	s_cselect_b64 s[0:1], -1, 0
	s_or_b64 s[0:1], s[6:7], s[0:1]
	s_and_b64 s[6:7], s[6:7], exec
	s_cselect_b32 s10, s10, s13
	s_cmpk_gt_i32 s14, 0xff
	s_cselect_b32 s12, s12, s33
	s_cmpk_eq_i32 s14, 0x100
	s_cselect_b64 s[6:7], -1, 0
	s_or_b64 s[42:43], s[42:43], s[6:7]
	s_and_b64 s[4:5], s[4:5], exec
	s_cselect_b32 s33, s33, s12
	s_and_b64 s[4:5], s[0:1], s[42:43]
	s_or_b64 s[4:5], s[8:9], s[4:5]
	s_and_b64 vcc, exec, s[4:5]
	s_cbranch_vccz .Lsel_m3
	s_branch .Lsel_exit
; #define DPP_ADDI(ctrl, rmask) v += __builtin_amdgcn_update_dpp(0, v, ctrl, rmask, 0xF, false)
; __device__ __forceinline__ int wave_sum_i_dpp(int v) {
;     ...
;     DPP_ADDI(0xB1, 0xF); DPP_ADDI(0x4E, 0xF); DPP_ADDI(0x141, 0xF); DPP_ADDI(0x140, 0xF); DPP_ADDI(0x142, 0xA); DPP_ADDI(0x143, 0xC);
;     ...
;     return __builtin_amdgcn_readlane(v, 63);
; }
; __device__ __forceinline__ void select_item(const Frame& F, int l, int samp, int b, int c, int qg) {
;     ...
;             const unsigned candA = prefixA | (1u << bit), candB = prefixB | (1u << bit), cA1 = candA - 1u, cB1 = candB - 1u; unsigned a4[4] = {0u, 0u, 0u, 0u}, b4[4] = {0u, 0u, 0u, 0u};
; #pragma unroll
;             for (int j = 0; j < 64; ++j) { a4[j & 3] += min(__builtin_elementwise_sub_sat(keyA[j], cA1), 1u); b4[j & 3] += min(__builtin_elementwise_sub_sat(keyB[j], cB1), 1u); }
;             const int cntA = wave_sum_i_dpp((int)((a4[0] + a4[1]) + (a4[2] + a4[3]))), cntB = wave_sum_i_dpp((int)((b4[0] + b4[1]) + (b4[2] + b4[3])));
;             if (!doneA) { if (cntA >= 256) prefixA = candA; if (cntA == 256) doneA = true; }
;             if (!doneB) { if (cntB >= 256) prefixB = candB; if (cntB == 256) doneB = true; }
;         }
.Lsel_m4:
	s_mov_b64 s[6:7], s[0:1]
	s_lshl_b32 s0, 1, s11
	s_or_b32 s13, s0, s10
	s_or_b32 s12, s0, s33
	s_add_i32 s14, s13, -1
	s_add_i32 s15, s12, -1
	s_cmp_eq_u32 s11, 0
	s_cselect_b64 s[8:9], -1, 0
	s_add_i32 s11, s11, -1
	s_mov_b64 s[4:5], s[42:43]
	s_cmp_lt_u32 s14, 0x7fffff
	s_cselect_b32 s0, 32, 0
	v_mov_b32_e32 v2, s0
	s_cmp_lt_u32 s15, 0x7fffff
	s_cselect_b32 s0, 32, 0
	v_mov_b32_e32 v3, s0
	v_cmp_lt_u32_e64 s[0:1], s14, v127
	v_cmp_lt_u32_e64 s[100:101], s15, v81
	v_cmp_lt_u32_e32 vcc, s14, v4
	v_cndmask_b32_e64 v132, 0, 1, s[0:1]
	v_cndmask_b32_e64 v133, 0, 1, s[100:101]
	v_addc_co_u32_e32 v2, vcc, v2, v132, vcc
	v_cmp_lt_u32_e32 vcc, s15, v6
	v_cmp_lt_u32_e64 s[0:1], s14, v65
	v_cmp_lt_u32_e64 s[100:101], s15, v7
	v_addc_co_u32_e32 v3, vcc, v3, v133, vcc
	v_cmp_lt_u32_e32 vcc, s14, v129
	v_cndmask_b32_e64 v132, 0, 1, s[0:1]
	v_cndmask_b32_e64 v133, 0, 1, s[100:101]
	v_addc_co_u32_e32 v2, vcc, v2, v132, vcc
	v_cmp_lt_u32_e32 vcc, s15, v8
	v_cmp_lt_u32_e64 s[0:1], s14, v70
	v_cmp_lt_u32_e64 s[100:101], s15, v9
	v_addc_co_u32_e32 v3, vcc, v3, v133, vcc
	v_cmp_lt_u32_e32 vcc, s14, v67
	v_cndmask_b32_e64 v132, 0, 1, s[0:1]
	v_cndmask_b32_e64 v133, 0, 1, s[100:101]
	v_addc_co_u32_e32 v2, vcc, v2, v132, vcc
	v_cmp_lt_u32_e32 vcc, s15, v10
	v_cmp_lt_u32_e64 s[0:1], s14, v5
	v_cmp_lt_u32_e64 s[100:101], s15, v11
	v_addc_co_u32_e32 v3, vcc, v3, v133, vcc
	v_cmp_lt_u32_e32 vcc, s14, v69
	v_cndmask_b32_e64 v132, 0, 1, s[0:1]
	v_cndmask_b32_e64 v133, 0, 1, s[100:101]
	v_addc_co_u32_e32 v2, vcc, v2, v132, vcc
	v_cmp_lt_u32_e32 vcc, s15, v12
	v_cmp_lt_u32_e64 s[0:1], s14, v66
	v_cmp_lt_u32_e64 s[100:101], s15, v17
	v_addc_co_u32_e32 v3, vcc, v3, v133, vcc
	v_cmp_lt_u32_e32 vcc, s14, v71
	v_cndmask_b32_e64 v132, 0, 1, s[0:1]
	v_cndmask_b32_e64 v133, 0, 1, s[100:101]
	v_addc_co_u32_e32 v2, vcc, v2, v132, vcc
	v_cmp_lt_u32_e32 vcc, s15, v18
	v_cmp_lt_u32_e64 s[0:1], s14, v79
	v_cmp_lt_u32_e64 s[100:101], s15, v19
	v_addc_co_u32_e32 v3, vcc, v3, v133, vcc
	v_cmp_lt_u32_e32 vcc, s14, v72
	v_cndmask_b32_e64 v132, 0, 1, s[0:1]
	v_cndmask_b32_e64 v133, 0, 1, s[100:101]
	v_addc_co_u32_e32 v2, vcc, v2, v132, vcc
	v_cmp_lt_u32_e32 vcc, s15, v20
	v_cmp_lt_u32_e64 s[0:1], s14, v76
	v_cmp_lt_u32_e64 s[100:101], s15, v25
	v_addc_co_u32_e32 v3, vcc, v3, v133, vcc
	v_cmp_lt_u32_e32 vcc, s14, v74
	v_cndmask_b32_e64 v132, 0, 1, s[0:1]
	v_cndmask_b32_e64 v133, 0, 1, s[100:101]
	v_addc_co_u32_e32 v2, vcc, v2, v132, vcc
	v_cmp_lt_u32_e32 vcc, s15, v26
	v_cmp_lt_u32_e64 s[0:1], s14, v78
	v_cmp_lt_u32_e64 s[100:101], s15, v27
	v_addc_co_u32_e32 v3, vcc, v3, v133, vcc
	v_cmp_lt_u32_e32 vcc, s14, v92
	v_cndmask_b32_e64 v132, 0, 1, s[0:1]
	v_cndmask_b32_e64 v133, 0, 1, s[100:101]
	v_addc_co_u32_e32 v2, vcc, v2, v132, vcc
	v_cmp_lt_u32_e32 vcc, s15, v28
	v_cmp_lt_u32_e64 s[0:1], s14, v86
	v_cmp_lt_u32_e64 s[100:101], s15, v83
	v_addc_co_u32_e32 v3, vcc, v3, v133, vcc
	v_cmp_lt_u32_e32 vcc, s14, v89
	v_cndmask_b32_e64 v132, 0, 1, s[0:1]
	v_cndmask_b32_e64 v133, 0, 1, s[100:101]
	v_addc_co_u32_e32 v2, vcc, v2, v132, vcc
	v_cmp_lt_u32_e32 vcc, s15, v15
	v_cmp_lt_u32_e64 s[0:1], s14, v88
	v_cmp_lt_u32_e64 s[100:101], s15, v23
	v_addc_co_u32_e32 v3, vcc, v3, v133, vcc
	v_cmp_lt_u32_e32 vcc, s14, v91
	v_cndmask_b32_e64 v132, 0, 1, s[0:1]
	v_cndmask_b32_e64 v133, 0, 1, s[100:101]
	v_addc_co_u32_e32 v2, vcc, v2, v132, vcc
	v_cmp_lt_u32_e32 vcc, s15, v31
	v_cmp_lt_u32_e64 s[0:1], s14, v128
	v_cmp_lt_u32_e64 s[100:101], s15, v82
	v_addc_co_u32_e32 v3, vcc, v3, v133, vcc
	v_cmp_lt_u32_e32 vcc, s14, v75
	v_cndmask_b32_e64 v132, 0, 1, s[0:1]
	v_cndmask_b32_e64 v133, 0, 1, s[100:101]
	v_addc_co_u32_e32 v2, vcc, v2, v132, vcc
	v_cmp_lt_u32_e32 vcc, s15, v16
	v_cmp_lt_u32_e64 s[0:1], s14, v87
	v_cmp_lt_u32_e64 s[100:101], s15, v24
	v_addc_co_u32_e32 v3, vcc, v3, v133, vcc
	v_cmp_lt_u32_e32 vcc, s14, v95
	v_cndmask_b32_e64 v132, 0, 1, s[0:1]
	v_cndmask_b32_e64 v133, 0, 1, s[100:101]
	v_addc_co_u32_e32 v2, vcc, v2, v132, vcc
	v_cmp_lt_u32_e32 vcc, s15, v32
	v_cmp_lt_u32_e64 s[0:1], s14, v131
	v_cmp_lt_u32_e64 s[100:101], s15, v85
	v_addc_co_u32_e32 v3, vcc, v3, v133, vcc
	v_cmp_lt_u32_e32 vcc, s14, v68
	v_cndmask_b32_e64 v132, 0, 1, s[0:1]
	v_cndmask_b32_e64 v133, 0, 1, s[100:101]
	v_addc_co_u32_e32 v2, vcc, v2, v132, vcc
	v_cmp_lt_u32_e32 vcc, s15, v13
	v_cmp_lt_u32_e64 s[0:1], s14, v77
	v_cmp_lt_u32_e64 s[100:101], s15, v21
	v_addc_co_u32_e32 v3, vcc, v3, v133, vcc
	v_cmp_lt_u32_e32 vcc, s14, v90
	v_cndmask_b32_e64 v132, 0, 1, s[0:1]
	v_cndmask_b32_e64 v133, 0, 1, s[100:101]
	v_addc_co_u32_e32 v2, vcc, v2, v132, vcc
	v_cmp_lt_u32_e32 vcc, s15, v29
	v_cmp_lt_u32_e64 s[0:1], s14, v130
	v_cmp_lt_u32_e64 s[100:101], s15, v84
	v_addc_co_u32_e32 v3, vcc, v3, v133, vcc
	v_cmp_lt_u32_e32 vcc, s14, v73
	v_cndmask_b32_e64 v132, 0, 1, s[0:1]
	v_cndmask_b32_e64 v133, 0, 1, s[100:101]
	v_addc_co_u32_e32 v2, vcc, v2, v132, vcc
	v_cmp_lt_u32_e32 vcc, s15, v14
	v_cmp_lt_u32_e64 s[0:1], s14, v80
	v_cmp_lt_u32_e64 s[100:101], s15, v22
	v_addc_co_u32_e32 v3, vcc, v3, v133, vcc
	v_cmp_lt_u32_e32 vcc, s14, v93
	v_cndmask_b32_e64 v132, 0, 1, s[0:1]
	v_cndmask_b32_e64 v133, 0, 1, s[100:101]
	v_addc_co_u32_e32 v2, vcc, v2, v132, vcc
	v_cmp_lt_u32_e32 vcc, s15, v30
	s_nop 1
	v_addc_co_u32_e32 v3, vcc, v3, v133, vcc
	v_lshl_add_u32 v2, v3, 16, v2
	s_nop 1
	v_add_u32_dpp v2, v2, v2 quad_perm:[1,0,3,2] row_mask:0xf bank_mask:0xf bound_ctrl:1
	s_nop 1
	v_add_u32_dpp v2, v2, v2 quad_perm:[2,3,0,1] row_mask:0xf bank_mask:0xf bound_ctrl:1
	s_nop 1
	v_add_u32_dpp v2, v2, v2 row_half_mirror row_mask:0xf bank_mask:0xf bound_ctrl:1
	s_nop 1
	v_add_u32_dpp v2, v2, v2 row_mirror row_mask:0xf bank_mask:0xf bound_ctrl:1
	s_nop 1
	v_add_u32_dpp v2, v2, v2 row_bcast:15 row_mask:0xa bank_mask:0xf
	s_nop 1
	v_add_u32_dpp v2, v2, v2 row_bcast:31 row_mask:0xc bank_mask:0xf
	s_nop 0
	v_readlane_b32 s0, v2, 63
	s_lshr_b32 s14, s0, 16
	s_and_b32 s0, s0, 0xffff
	s_cmpk_gt_i32 s0, 0xff
	s_cselect_b32 s13, s13, s10
	s_cmpk_eq_i32 s0, 0x100
	s_cselect_b64 s[0:1], -1, 0
	s_or_b64 s[0:1], s[6:7], s[0:1]
	s_and_b64 s[6:7], s[6:7], exec
	s_cselect_b32 s10, s10, s13
	s_cmpk_gt_i32 s14, 0xff
	s_cselect_b32 s12, s12, s33
	s_cmpk_eq_i32 s14, 0x100
	s_cselect_b64 s[6:7], -1, 0
	s_or_b64 s[42:43], s[42:43], s[6:7]
	s_and_b64 s[4:5], s[4:5], exec
	s_cselect_b32 s33, s33, s12
	s_and_b64 s[4:5], s[0:1], s[42:43]
	s_or_b64 s[4:5], s[8:9], s[4:5]
	s_and_b64 vcc, exec, s[4:5]
	s_cbranch_vccz .Lsel_m4
	s_branch .Lsel_exit
; __device__ __forceinline__ void select_item(const Frame& F, int l, int samp, int b, int c, int qg) {
;     ...
;             const unsigned candA = prefixA | (1u << bit), candB = prefixB | (1u << bit), cA1 = candA - 1u, cB1 = candB - 1u; unsigned a4[4] = {0u, 0u, 0u, 0u}, b4[4] = {0u, 0u, 0u, 0u};
; #pragma unroll
;             for (int j = 0; j < 64; ++j) { a4[j & 3] += min(__builtin_elementwise_sub_sat(keyA[j], cA1), 1u); b4[j & 3] += min(__builtin_elementwise_sub_sat(keyB[j], cB1), 1u); }
;             const int cntA = wave_sum_i_dpp((int)((a4[0] + a4[1]) + (a4[2] + a4[3]))), cntB = wave_sum_i_dpp((int)((b4[0] + b4[1]) + (b4[2] + b4[3])));
;             if (!doneA) { if (cntA >= 256) prefixA = candA; if (cntA == 256) doneA = true; }
.Lsel_m5:
	s_mov_b64 s[6:7], s[0:1]
	s_lshl_b32 s0, 1, s11
	s_or_b32 s13, s0, s10
	s_or_b32 s12, s0, s33
	s_add_i32 s14, s13, -1
	s_add_i32 s15, s12, -1
	s_cmp_eq_u32 s11, 0
	s_cselect_b64 s[8:9], -1, 0
	s_add_i32 s11, s11, -1
	s_mov_b64 s[4:5], s[42:43]
	s_cmp_lt_u32 s14, 0x7fffff
	s_cselect_b32 s0, 24, 0
	v_mov_b32_e32 v2, s0
	s_cmp_lt_u32 s15, 0x7fffff
	s_cselect_b32 s0, 24, 0
	v_mov_b32_e32 v3, s0
	v_cmp_lt_u32_e64 s[0:1], s14, v127
	v_cmp_lt_u32_e64 s[100:101], s15, v81
	v_cmp_lt_u32_e32 vcc, s14, v4
	v_cndmask_b32_e64 v132, 0, 1, s[0:1]
	v_cndmask_b32_e64 v133, 0, 1, s[100:101]
	v_addc_co_u32_e32 v2, vcc, v2, v132, vcc
	v_cmp_lt_u32_e32 vcc, s15, v6
	v_cmp_lt_u32_e64 s[0:1], s14, v65
	v_cmp_lt_u32_e64 s[100:101], s15, v7
	v_addc_co_u32_e32 v3, vcc, v3, v133, vcc
	v_cmp_lt_u32_e32 vcc, s14, v129
	v_cndmask_b32_e64 v132, 0, 1, s[0:1]
	v_cndmask_b32_e64 v133, 0, 1, s[100:101]
	v_addc_co_u32_e32 v2, vcc, v2, v132, vcc
	v_cmp_lt_u32_e32 vcc, s15, v8
	v_cmp_lt_u32_e64 s[0:1], s14, v70
	v_cmp_lt_u32_e64 s[100:101], s15, v9
	v_addc_co_u32_e32 v3, vcc, v3, v133, vcc
	v_cmp_lt_u32_e32 vcc, s14, v67
	v_cndmask_b32_e64 v132, 0, 1, s[0:1]
	v_cndmask_b32_e64 v133, 0, 1, s[100:101]
	v_addc_co_u32_e32 v2, vcc, v2, v132, vcc
	v_cmp_lt_u32_e32 vcc, s15, v10
	v_cmp_lt_u32_e64 s[0:1], s14, v5
	v_cmp_lt_u32_e64 s[100:101], s15, v11
	v_addc_co_u32_e32 v3, vcc, v3, v133, vcc
	v_cmp_lt_u32_e32 vcc, s14, v69
	v_cndmask_b32_e64 v132, 0, 1, s[0:1]
	v_cndmask_b32_e64 v133, 0, 1, s[100:101]
	v_addc_co_u32_e32 v2, vcc, v2, v132, vcc
	v_cmp_lt_u32_e32 vcc, s15, v12
	v_cmp_lt_u32_e64 s[0:1], s14, v66
	v_cmp_lt_u32_e64 s[100:101], s15, v17
	v_addc_co_u32_e32 v3, vcc, v3, v133, vcc
	v_cmp_lt_u32_e32 vcc, s14, v71
	v_cndmask_b32_e64 v132, 0, 1, s[0:1]
	v_cndmask_b32_e64 v133, 0, 1, s[100:101]
	v_addc_co_u32_e32 v2, vcc, v2, v132, vcc
	v_cmp_lt_u32_e32 vcc, s15, v18
	v_cmp_lt_u32_e64 s[0:1], s14, v79
	v_cmp_lt_u32_e64 s[100:101], s15, v19
	v_addc_co_u32_e32 v3, vcc, v3, v133, vcc
	v_cmp_lt_u32_e32 vcc, s14, v72
	v_cndmask_b32_e64 v132, 0, 1, s[0:1]
	v_cndmask_b32_e64 v133, 0, 1, s[100:101]
	v_addc_co_u32_e32 v2, vcc, v2, v132, vcc
	v_cmp_lt_u32_e32 vcc, s15, v20
	v_cmp_lt_u32_e64 s[0:1], s14, v76
	v_cmp_lt_u32_e64 s[100:101], s15, v25
	v_addc_co_u32_e32 v3, vcc, v3, v133, vcc
	v_cmp_lt_u32_e32 vcc, s14, v74
	v_cndmask_b32_e64 v132, 0, 1, s[0:1]
	v_cndmask_b32_e64 v133, 0, 1, s[100:101]
	v_addc_co_u32_e32 v2, vcc, v2, v132, vcc
	v_cmp_lt_u32_e32 vcc, s15, v26
	v_cmp_lt_u32_e64 s[0:1], s14, v78
	v_cmp_lt_u32_e64 s[100:101], s15, v27
	v_addc_co_u32_e32 v3, vcc, v3, v133, vcc
	v_cmp_lt_u32_e32 vcc, s14, v92
	v_cndmask_b32_e64 v132, 0, 1, s[0:1]
	v_cndmask_b32_e64 v133, 0, 1, s[100:101]
	v_addc_co_u32_e32 v2, vcc, v2, v132, vcc
	v_cmp_lt_u32_e32 vcc, s15, v28
	v_cmp_lt_u32_e64 s[0:1], s14, v86
	v_cmp_lt_u32_e64 s[100:101], s15, v33
	v_addc_co_u32_e32 v3, vcc, v3, v133, vcc
	v_cmp_lt_u32_e32 vcc, s14, v89
	v_cndmask_b32_e64 v132, 0, 1, s[0:1]
	v_cndmask_b32_e64 v133, 0, 1, s[100:101]
	v_addc_co_u32_e32 v2, vcc, v2, v132, vcc
	v_cmp_lt_u32_e32 vcc, s15, v34
	v_cmp_lt_u32_e64 s[0:1], s14, v88
	v_cmp_lt_u32_e64 s[100:101], s15, v35
	v_addc_co_u32_e32 v3, vcc, v3, v133, vcc
	v_cmp_lt_u32_e32 vcc, s14, v91
	v_cndmask_b32_e64 v132, 0, 1, s[0:1]
	v_cndmask_b32_e64 v133, 0, 1, s[100:101]
	v_addc_co_u32_e32 v2, vcc, v2, v132, vcc
	v_cmp_lt_u32_e32 vcc, s15, v36
	v_cmp_lt_u32_e64 s[0:1], s14, v100
	v_cmp_lt_u32_e64 s[100:101], s15, v83
	v_addc_co_u32_e32 v3, vcc, v3, v133, vcc
	v_cmp_lt_u32_e32 vcc, s14, v94
	v_cndmask_b32_e64 v132, 0, 1, s[0:1]
	v_cndmask_b32_e64 v133, 0, 1, s[100:101]
	v_addc_co_u32_e32 v2, vcc, v2, v132, vcc
	v_cmp_lt_u32_e32 vcc, s15, v15
	v_cmp_lt_u32_e64 s[0:1], s14, v97
	v_cmp_lt_u32_e64 s[100:101], s15, v23
	v_addc_co_u32_e32 v3, vcc, v3, v133, vcc
	v_cmp_lt_u32_e32 vcc, s14, v96
	v_cndmask_b32_e64 v132, 0, 1, s[0:1]
	v_cndmask_b32_e64 v133, 0, 1, s[100:101]
	v_addc_co_u32_e32 v2, vcc, v2, v132, vcc
	v_cmp_lt_u32_e32 vcc, s15, v31
	v_cmp_lt_u32_e64 s[0:1], s14, v99
	v_cmp_lt_u32_e64 s[100:101], s15, v39
	v_addc_co_u32_e32 v3, vcc, v3, v133, vcc
	v_cmp_lt_u32_e32 vcc, s14, v128
	v_cndmask_b32_e64 v132, 0, 1, s[0:1]
	v_cndmask_b32_e64 v133, 0, 1, s[100:101]
	v_addc_co_u32_e32 v2, vcc, v2, v132, vcc
	v_cmp_lt_u32_e32 vcc, s15, v82
	v_cmp_lt_u32_e64 s[0:1], s14, v75
	v_cmp_lt_u32_e64 s[100:101], s15, v16
	v_addc_co_u32_e32 v3, vcc, v3, v133, vcc
	v_cmp_lt_u32_e32 vcc, s14, v87
	v_cndmask_b32_e64 v132, 0, 1, s[0:1]
	v_cndmask_b32_e64 v133, 0, 1, s[100:101]
	v_addc_co_u32_e32 v2, vcc, v2, v132, vcc
	v_cmp_lt_u32_e32 vcc, s15, v24
	v_cmp_lt_u32_e64 s[0:1], s14, v95
	v_cmp_lt_u32_e64 s[100:101], s15, v32
	v_addc_co_u32_e32 v3, vcc, v3, v133, vcc
	v_cmp_lt_u32_e32 vcc, s14, v103
	v_cndmask_b32_e64 v132, 0, 1, s[0:1]
	v_cndmask_b32_e64 v133, 0, 1, s[100:101]
	v_addc_co_u32_e32 v2, vcc, v2, v132, vcc
	v_cmp_lt_u32_e32 vcc, s15, v40
	v_cmp_lt_u32_e64 s[0:1], s14, v131
	v_cmp_lt_u32_e64 s[100:101], s15, v85
	v_addc_co_u32_e32 v3, vcc, v3, v133, vcc
	v_cmp_lt_u32_e32 vcc, s14, v68
	v_cndmask_b32_e64 v132, 0, 1, s[0:1]
	v_cndmask_b32_e64 v133, 0, 1, s[100:101]
	v_addc_co_u32_e32 v2, vcc, v2, v132, vcc
	v_cmp_lt_u32_e32 vcc, s15, v13
	v_cmp_lt_u32_e64 s[0:1], s14, v77
	v_cmp_lt_u32_e64 s[100:101], s15, v21
	v_addc_co_u32_e32 v3, vcc, v3, v133, vcc
	v_cmp_lt_u32_e32 vcc, s14, v90
	v_cndmask_b32_e64 v132, 0, 1, s[0:1]
	v_cndmask_b32_e64 v133, 0, 1, s[100:101]
	v_addc_co_u32_e32 v2, vcc, v2, v132, vcc
	v_cmp_lt_u32_e32 vcc, s15, v29
	v_cmp_lt_u32_e64 s[0:1], s14, v98
	v_cmp_lt_u32_e64 s[100:101], s15, v37
	v_addc_co_u32_e32 v3, vcc, v3, v133, vcc
	v_cmp_lt_u32_e32 vcc, s14, v130
; #define DPP_ADDI(ctrl, rmask) v += __builtin_amdgcn_update_dpp(0, v, ctrl, rmask, 0xF, false)
; __device__ __forceinline__ int wave_sum_i_dpp(int v) {
;     ...
;     DPP_ADDI(0xB1, 0xF); DPP_ADDI(0x4E, 0xF); DPP_ADDI(0x141, 0xF); DPP_ADDI(0x140, 0xF); DPP_ADDI(0x142, 0xA); DPP_ADDI(0x143, 0xC);
;     ...
;     return __builtin_amdgcn_readlane(v, 63);
; }
; __device__ __forceinline__ void select_item(const Frame& F, int l, int samp, int b, int c, int qg) {
;     ...
;             const unsigned candA = prefixA | (1u << bit), candB = prefixB | (1u << bit), cA1 = candA - 1u, cB1 = candB - 1u; unsigned a4[4] = {0u, 0u, 0u, 0u}, b4[4] = {0u, 0u, 0u, 0u};
; #pragma unroll
;             for (int j = 0; j < 64; ++j) { a4[j & 3] += min(__builtin_elementwise_sub_sat(keyA[j], cA1), 1u); b4[j & 3] += min(__builtin_elementwise_sub_sat(keyB[j], cB1), 1u); }
;             const int cntA = wave_sum_i_dpp((int)((a4[0] + a4[1]) + (a4[2] + a4[3]))), cntB = wave_sum_i_dpp((int)((b4[0] + b4[1]) + (b4[2] + b4[3])));
;             if (!doneA) { if (cntA >= 256) prefixA = candA; if (cntA == 256) doneA = true; }
;             if (!doneB) { if (cntB >= 256) prefixB = candB; if (cntB == 256) doneB = true; }
;         }
	v_cndmask_b32_e64 v132, 0, 1, s[0:1]
	v_cndmask_b32_e64 v133, 0, 1, s[100:101]
	v_addc_co_u32_e32 v2, vcc, v2, v132, vcc
	v_cmp_lt_u32_e32 vcc, s15, v84
	v_cmp_lt_u32_e64 s[0:1], s14, v73
	v_cmp_lt_u32_e64 s[100:101], s15, v14
	v_addc_co_u32_e32 v3, vcc, v3, v133, vcc
	v_cmp_lt_u32_e32 vcc, s14, v80
	v_cndmask_b32_e64 v132, 0, 1, s[0:1]
	v_cndmask_b32_e64 v133, 0, 1, s[100:101]
	v_addc_co_u32_e32 v2, vcc, v2, v132, vcc
	v_cmp_lt_u32_e32 vcc, s15, v22
	v_cmp_lt_u32_e64 s[0:1], s14, v93
	v_cmp_lt_u32_e64 s[100:101], s15, v30
	v_addc_co_u32_e32 v3, vcc, v3, v133, vcc
	v_cmp_lt_u32_e32 vcc, s14, v101
	v_cndmask_b32_e64 v132, 0, 1, s[0:1]
	v_cndmask_b32_e64 v133, 0, 1, s[100:101]
	v_addc_co_u32_e32 v2, vcc, v2, v132, vcc
	v_cmp_lt_u32_e32 vcc, s15, v38
	s_nop 1
	v_addc_co_u32_e32 v3, vcc, v3, v133, vcc
	v_lshl_add_u32 v2, v3, 16, v2
	s_nop 1
	v_add_u32_dpp v2, v2, v2 quad_perm:[1,0,3,2] row_mask:0xf bank_mask:0xf bound_ctrl:1
	s_nop 1
	v_add_u32_dpp v2, v2, v2 quad_perm:[2,3,0,1] row_mask:0xf bank_mask:0xf bound_ctrl:1
	s_nop 1
	v_add_u32_dpp v2, v2, v2 row_half_mirror row_mask:0xf bank_mask:0xf bound_ctrl:1
	s_nop 1
	v_add_u32_dpp v2, v2, v2 row_mirror row_mask:0xf bank_mask:0xf bound_ctrl:1
	s_nop 1
	v_add_u32_dpp v2, v2, v2 row_bcast:15 row_mask:0xa bank_mask:0xf
	s_nop 1
	v_add_u32_dpp v2, v2, v2 row_bcast:31 row_mask:0xc bank_mask:0xf
	s_nop 0
	v_readlane_b32 s0, v2, 63
	s_lshr_b32 s14, s0, 16
	s_and_b32 s0, s0, 0xffff
	s_cmpk_gt_i32 s0, 0xff
	s_cselect_b32 s13, s13, s10
	s_cmpk_eq_i32 s0, 0x100
	s_cselect_b64 s[0:1], -1, 0
	s_or_b64 s[0:1], s[6:7], s[0:1]
	s_and_b64 s[6:7], s[6:7], exec
	s_cselect_b32 s10, s10, s13
	s_cmpk_gt_i32 s14, 0xff
	s_cselect_b32 s12, s12, s33
	s_cmpk_eq_i32 s14, 0x100
	s_cselect_b64 s[6:7], -1, 0
	s_or_b64 s[42:43], s[42:43], s[6:7]
	s_and_b64 s[4:5], s[4:5], exec
	s_cselect_b32 s33, s33, s12
	s_and_b64 s[4:5], s[0:1], s[42:43]
	s_or_b64 s[4:5], s[8:9], s[4:5]
	s_and_b64 vcc, exec, s[4:5]
	s_cbranch_vccz .Lsel_m5
	s_branch .Lsel_exit
.Lsel_m6:
	s_mov_b64 s[6:7], s[0:1]
	s_lshl_b32 s0, 1, s11
	s_or_b32 s13, s0, s10
	s_or_b32 s12, s0, s33
	s_add_i32 s14, s13, -1
	s_add_i32 s15, s12, -1
	s_cmp_eq_u32 s11, 0
	s_cselect_b64 s[8:9], -1, 0
	s_add_i32 s11, s11, -1
	s_mov_b64 s[4:5], s[42:43]
	s_cmp_lt_u32 s14, 0x7fffff
	s_cselect_b32 s0, 16, 0
	v_mov_b32_e32 v2, s0
	s_cmp_lt_u32 s15, 0x7fffff
	s_cselect_b32 s0, 16, 0
	v_mov_b32_e32 v3, s0
	v_cmp_lt_u32_e64 s[0:1], s14, v127
	v_cmp_lt_u32_e64 s[100:101], s15, v81
	v_cmp_lt_u32_e32 vcc, s14, v4
	v_cndmask_b32_e64 v132, 0, 1, s[0:1]
	v_cndmask_b32_e64 v133, 0, 1, s[100:101]
	v_addc_co_u32_e32 v2, vcc, v2, v132, vcc
	v_cmp_lt_u32_e32 vcc, s15, v6
	v_cmp_lt_u32_e64 s[0:1], s14, v65
	v_cmp_lt_u32_e64 s[100:101], s15, v7
	v_addc_co_u32_e32 v3, vcc, v3, v133, vcc
	v_cmp_lt_u32_e32 vcc, s14, v129
	v_cndmask_b32_e64 v132, 0, 1, s[0:1]
	v_cndmask_b32_e64 v133, 0, 1, s[100:101]
	v_addc_co_u32_e32 v2, vcc, v2, v132, vcc
	v_cmp_lt_u32_e32 vcc, s15, v8
	v_cmp_lt_u32_e64 s[0:1], s14, v70
	v_cmp_lt_u32_e64 s[100:101], s15, v9
	v_addc_co_u32_e32 v3, vcc, v3, v133, vcc
	v_cmp_lt_u32_e32 vcc, s14, v67
	v_cndmask_b32_e64 v132, 0, 1, s[0:1]
	v_cndmask_b32_e64 v133, 0, 1, s[100:101]
	v_addc_co_u32_e32 v2, vcc, v2, v132, vcc
	v_cmp_lt_u32_e32 vcc, s15, v10
	v_cmp_lt_u32_e64 s[0:1], s14, v5
	v_cmp_lt_u32_e64 s[100:101], s15, v11
	v_addc_co_u32_e32 v3, vcc, v3, v133, vcc
	v_cmp_lt_u32_e32 vcc, s14, v69
	v_cndmask_b32_e64 v132, 0, 1, s[0:1]
	v_cndmask_b32_e64 v133, 0, 1, s[100:101]
	v_addc_co_u32_e32 v2, vcc, v2, v132, vcc
	v_cmp_lt_u32_e32 vcc, s15, v12
	v_cmp_lt_u32_e64 s[0:1], s14, v66
	v_cmp_lt_u32_e64 s[100:101], s15, v17
	v_addc_co_u32_e32 v3, vcc, v3, v133, vcc
	v_cmp_lt_u32_e32 vcc, s14, v71
	v_cndmask_b32_e64 v132, 0, 1, s[0:1]
	v_cndmask_b32_e64 v133, 0, 1, s[100:101]
	v_addc_co_u32_e32 v2, vcc, v2, v132, vcc
	v_cmp_lt_u32_e32 vcc, s15, v18
	v_cmp_lt_u32_e64 s[0:1], s14, v79
	v_cmp_lt_u32_e64 s[100:101], s15, v19
	v_addc_co_u32_e32 v3, vcc, v3, v133, vcc
	v_cmp_lt_u32_e32 vcc, s14, v72
	v_cndmask_b32_e64 v132, 0, 1, s[0:1]
	v_cndmask_b32_e64 v133, 0, 1, s[100:101]
	v_addc_co_u32_e32 v2, vcc, v2, v132, vcc
	v_cmp_lt_u32_e32 vcc, s15, v20
	v_cmp_lt_u32_e64 s[0:1], s14, v76
	v_cmp_lt_u32_e64 s[100:101], s15, v25
	v_addc_co_u32_e32 v3, vcc, v3, v133, vcc
	v_cmp_lt_u32_e32 vcc, s14, v74
	v_cndmask_b32_e64 v132, 0, 1, s[0:1]
	v_cndmask_b32_e64 v133, 0, 1, s[100:101]
	v_addc_co_u32_e32 v2, vcc, v2, v132, vcc
	v_cmp_lt_u32_e32 vcc, s15, v26
	v_cmp_lt_u32_e64 s[0:1], s14, v78
	v_cmp_lt_u32_e64 s[100:101], s15, v27
	v_addc_co_u32_e32 v3, vcc, v3, v133, vcc
	v_cmp_lt_u32_e32 vcc, s14, v92
	v_cndmask_b32_e64 v132, 0, 1, s[0:1]
	v_cndmask_b32_e64 v133, 0, 1, s[100:101]
	v_addc_co_u32_e32 v2, vcc, v2, v132, vcc
	v_cmp_lt_u32_e32 vcc, s15, v28
	v_cmp_lt_u32_e64 s[0:1], s14, v86
	v_cmp_lt_u32_e64 s[100:101], s15, v33
	v_addc_co_u32_e32 v3, vcc, v3, v133, vcc
	v_cmp_lt_u32_e32 vcc, s14, v89
	v_cndmask_b32_e64 v132, 0, 1, s[0:1]
	v_cndmask_b32_e64 v133, 0, 1, s[100:101]
	v_addc_co_u32_e32 v2, vcc, v2, v132, vcc
	v_cmp_lt_u32_e32 vcc, s15, v34
	v_cmp_lt_u32_e64 s[0:1], s14, v88
	v_cmp_lt_u32_e64 s[100:101], s15, v35
	v_addc_co_u32_e32 v3, vcc, v3, v133, vcc
	v_cmp_lt_u32_e32 vcc, s14, v91
	v_cndmask_b32_e64 v132, 0, 1, s[0:1]
	v_cndmask_b32_e64 v133, 0, 1, s[100:101]
	v_addc_co_u32_e32 v2, vcc, v2, v132, vcc
	v_cmp_lt_u32_e32 vcc, s15, v36
	v_cmp_lt_u32_e64 s[0:1], s14, v100
	v_cmp_lt_u32_e64 s[100:101], s15, v41
	v_addc_co_u32_e32 v3, vcc, v3, v133, vcc
	v_cmp_lt_u32_e32 vcc, s14, v94
	v_cndmask_b32_e64 v132, 0, 1, s[0:1]
	v_cndmask_b32_e64 v133, 0, 1, s[100:101]
	v_addc_co_u32_e32 v2, vcc, v2, v132, vcc
; #define DPP_ADDI(ctrl, rmask) v += __builtin_amdgcn_update_dpp(0, v, ctrl, rmask, 0xF, false)
; __device__ __forceinline__ int wave_sum_i_dpp(int v) {
;     ...
;     DPP_ADDI(0xB1, 0xF); DPP_ADDI(0x4E, 0xF); DPP_ADDI(0x141, 0xF); DPP_ADDI(0x140, 0xF); DPP_ADDI(0x142, 0xA); DPP_ADDI(0x143, 0xC);
;     ...
;     return __builtin_amdgcn_readlane(v, 63);
; }
; __device__ __forceinline__ void select_item(const Frame& F, int l, int samp, int b, int c, int qg) {
;     ...
;             const unsigned candA = prefixA | (1u << bit), candB = prefixB | (1u << bit), cA1 = candA - 1u, cB1 = candB - 1u; unsigned a4[4] = {0u, 0u, 0u, 0u}, b4[4] = {0u, 0u, 0u, 0u};
; #pragma unroll
;             for (int j = 0; j < 64; ++j) { a4[j & 3] += min(__builtin_elementwise_sub_sat(keyA[j], cA1), 1u); b4[j & 3] += min(__builtin_elementwise_sub_sat(keyB[j], cB1), 1u); }
;             const int cntA = wave_sum_i_dpp((int)((a4[0] + a4[1]) + (a4[2] + a4[3]))), cntB = wave_sum_i_dpp((int)((b4[0] + b4[1]) + (b4[2] + b4[3])));
;             if (!doneA) { if (cntA >= 256) prefixA = candA; if (cntA == 256) doneA = true; }
;             if (!doneB) { if (cntB >= 256) prefixB = candB; if (cntB == 256) doneB = true; }
;         }
	v_cmp_lt_u32_e32 vcc, s15, v42
	v_cmp_lt_u32_e64 s[0:1], s14, v97
	v_cmp_lt_u32_e64 s[100:101], s15, v43
	v_addc_co_u32_e32 v3, vcc, v3, v133, vcc
	v_cmp_lt_u32_e32 vcc, s14, v96
	v_cndmask_b32_e64 v132, 0, 1, s[0:1]
	v_cndmask_b32_e64 v133, 0, 1, s[100:101]
	v_addc_co_u32_e32 v2, vcc, v2, v132, vcc
	v_cmp_lt_u32_e32 vcc, s15, v44
	v_cmp_lt_u32_e64 s[0:1], s14, v99
	v_cmp_lt_u32_e64 s[100:101], s15, v83
	v_addc_co_u32_e32 v3, vcc, v3, v133, vcc
	v_cmp_lt_u32_e32 vcc, s14, v108
	v_cndmask_b32_e64 v132, 0, 1, s[0:1]
	v_cndmask_b32_e64 v133, 0, 1, s[100:101]
	v_addc_co_u32_e32 v2, vcc, v2, v132, vcc
	v_cmp_lt_u32_e32 vcc, s15, v15
	v_cmp_lt_u32_e64 s[0:1], s14, v102
	v_cmp_lt_u32_e64 s[100:101], s15, v23
	v_addc_co_u32_e32 v3, vcc, v3, v133, vcc
	v_cmp_lt_u32_e32 vcc, s14, v105
	v_cndmask_b32_e64 v132, 0, 1, s[0:1]
	v_cndmask_b32_e64 v133, 0, 1, s[100:101]
	v_addc_co_u32_e32 v2, vcc, v2, v132, vcc
	v_cmp_lt_u32_e32 vcc, s15, v31
	v_cmp_lt_u32_e64 s[0:1], s14, v104
	v_cmp_lt_u32_e64 s[100:101], s15, v39
	v_addc_co_u32_e32 v3, vcc, v3, v133, vcc
	v_cmp_lt_u32_e32 vcc, s14, v107
	v_cndmask_b32_e64 v132, 0, 1, s[0:1]
	v_cndmask_b32_e64 v133, 0, 1, s[100:101]
	v_addc_co_u32_e32 v2, vcc, v2, v132, vcc
	v_cmp_lt_u32_e32 vcc, s15, v47
	v_cmp_lt_u32_e64 s[0:1], s14, v128
	v_cmp_lt_u32_e64 s[100:101], s15, v82
	v_addc_co_u32_e32 v3, vcc, v3, v133, vcc
	v_cmp_lt_u32_e32 vcc, s14, v75
	v_cndmask_b32_e64 v132, 0, 1, s[0:1]
	v_cndmask_b32_e64 v133, 0, 1, s[100:101]
	v_addc_co_u32_e32 v2, vcc, v2, v132, vcc
	v_cmp_lt_u32_e32 vcc, s15, v16
	v_cmp_lt_u32_e64 s[0:1], s14, v87
	v_cmp_lt_u32_e64 s[100:101], s15, v24
	v_addc_co_u32_e32 v3, vcc, v3, v133, vcc
	v_cmp_lt_u32_e32 vcc, s14, v95
	v_cndmask_b32_e64 v132, 0, 1, s[0:1]
	v_cndmask_b32_e64 v133, 0, 1, s[100:101]
	v_addc_co_u32_e32 v2, vcc, v2, v132, vcc
	v_cmp_lt_u32_e32 vcc, s15, v32
	v_cmp_lt_u32_e64 s[0:1], s14, v103
	v_cmp_lt_u32_e64 s[100:101], s15, v40
	v_addc_co_u32_e32 v3, vcc, v3, v133, vcc
	v_cmp_lt_u32_e32 vcc, s14, v111
	v_cndmask_b32_e64 v132, 0, 1, s[0:1]
	v_cndmask_b32_e64 v133, 0, 1, s[100:101]
	v_addc_co_u32_e32 v2, vcc, v2, v132, vcc
	v_cmp_lt_u32_e32 vcc, s15, v48
	v_cmp_lt_u32_e64 s[0:1], s14, v131
	v_cmp_lt_u32_e64 s[100:101], s15, v85
	v_addc_co_u32_e32 v3, vcc, v3, v133, vcc
	v_cmp_lt_u32_e32 vcc, s14, v68
	v_cndmask_b32_e64 v132, 0, 1, s[0:1]
	v_cndmask_b32_e64 v133, 0, 1, s[100:101]
	v_addc_co_u32_e32 v2, vcc, v2, v132, vcc
	v_cmp_lt_u32_e32 vcc, s15, v13
	v_cmp_lt_u32_e64 s[0:1], s14, v77
	v_cmp_lt_u32_e64 s[100:101], s15, v21
	v_addc_co_u32_e32 v3, vcc, v3, v133, vcc
	v_cmp_lt_u32_e32 vcc, s14, v90
	v_cndmask_b32_e64 v132, 0, 1, s[0:1]
	v_cndmask_b32_e64 v133, 0, 1, s[100:101]
	v_addc_co_u32_e32 v2, vcc, v2, v132, vcc
	v_cmp_lt_u32_e32 vcc, s15, v29
	v_cmp_lt_u32_e64 s[0:1], s14, v98
	v_cmp_lt_u32_e64 s[100:101], s15, v37
	v_addc_co_u32_e32 v3, vcc, v3, v133, vcc
	v_cmp_lt_u32_e32 vcc, s14, v106
	v_cndmask_b32_e64 v132, 0, 1, s[0:1]
	v_cndmask_b32_e64 v133, 0, 1, s[100:101]
	v_addc_co_u32_e32 v2, vcc, v2, v132, vcc
	v_cmp_lt_u32_e32 vcc, s15, v45
	v_cmp_lt_u32_e64 s[0:1], s14, v130
	v_cmp_lt_u32_e64 s[100:101], s15, v84
	v_addc_co_u32_e32 v3, vcc, v3, v133, vcc
	v_cmp_lt_u32_e32 vcc, s14, v73
	v_cndmask_b32_e64 v132, 0, 1, s[0:1]
	v_cndmask_b32_e64 v133, 0, 1, s[100:101]
	v_addc_co_u32_e32 v2, vcc, v2, v132, vcc
	v_cmp_lt_u32_e32 vcc, s15, v14
	v_cmp_lt_u32_e64 s[0:1], s14, v80
	v_cmp_lt_u32_e64 s[100:101], s15, v22
	v_addc_co_u32_e32 v3, vcc, v3, v133, vcc
	v_cmp_lt_u32_e32 vcc, s14, v93
	v_cndmask_b32_e64 v132, 0, 1, s[0:1]
	v_cndmask_b32_e64 v133, 0, 1, s[100:101]
	v_addc_co_u32_e32 v2, vcc, v2, v132, vcc
	v_cmp_lt_u32_e32 vcc, s15, v30
	v_cmp_lt_u32_e64 s[0:1], s14, v101
	v_cmp_lt_u32_e64 s[100:101], s15, v38
	v_addc_co_u32_e32 v3, vcc, v3, v133, vcc
	v_cmp_lt_u32_e32 vcc, s14, v109
	v_cndmask_b32_e64 v132, 0, 1, s[0:1]
	v_cndmask_b32_e64 v133, 0, 1, s[100:101]
	v_addc_co_u32_e32 v2, vcc, v2, v132, vcc
	v_cmp_lt_u32_e32 vcc, s15, v46
	s_nop 1
	v_addc_co_u32_e32 v3, vcc, v3, v133, vcc
	v_lshl_add_u32 v2, v3, 16, v2
	s_nop 1
	v_add_u32_dpp v2, v2, v2 quad_perm:[1,0,3,2] row_mask:0xf bank_mask:0xf bound_ctrl:1
	s_nop 1
	v_add_u32_dpp v2, v2, v2 quad_perm:[2,3,0,1] row_mask:0xf bank_mask:0xf bound_ctrl:1
	s_nop 1
	v_add_u32_dpp v2, v2, v2 row_half_mirror row_mask:0xf bank_mask:0xf bound_ctrl:1
	s_nop 1
	v_add_u32_dpp v2, v2, v2 row_mirror row_mask:0xf bank_mask:0xf bound_ctrl:1
	s_nop 1
	v_add_u32_dpp v2, v2, v2 row_bcast:15 row_mask:0xa bank_mask:0xf
	s_nop 1
	v_add_u32_dpp v2, v2, v2 row_bcast:31 row_mask:0xc bank_mask:0xf
	s_nop 0
	v_readlane_b32 s0, v2, 63
	s_lshr_b32 s14, s0, 16
	s_and_b32 s0, s0, 0xffff
	s_cmpk_gt_i32 s0, 0xff
	s_cselect_b32 s13, s13, s10
	s_cmpk_eq_i32 s0, 0x100
	s_cselect_b64 s[0:1], -1, 0
	s_or_b64 s[0:1], s[6:7], s[0:1]
	s_and_b64 s[6:7], s[6:7], exec
	s_cselect_b32 s10, s10, s13
	s_cmpk_gt_i32 s14, 0xff
	s_cselect_b32 s12, s12, s33
	s_cmpk_eq_i32 s14, 0x100
	s_cselect_b64 s[6:7], -1, 0
	s_or_b64 s[42:43], s[42:43], s[6:7]
	s_and_b64 s[4:5], s[4:5], exec
	s_cselect_b32 s33, s33, s12
	s_and_b64 s[4:5], s[0:1], s[42:43]
	s_or_b64 s[4:5], s[8:9], s[4:5]
	s_and_b64 vcc, exec, s[4:5]
	s_cbranch_vccz .Lsel_m6
	s_branch .Lsel_exit
; __device__ __forceinline__ void select_item(const Frame& F, int l, int samp, int b, int c, int qg) {
;     ...
;             const unsigned candA = prefixA | (1u << bit), candB = prefixB | (1u << bit), cA1 = candA - 1u, cB1 = candB - 1u; unsigned a4[4] = {0u, 0u, 0u, 0u}, b4[4] = {0u, 0u, 0u, 0u};
; #pragma unroll
;             for (int j = 0; j < 64; ++j) { a4[j & 3] += min(__builtin_elementwise_sub_sat(keyA[j], cA1), 1u); b4[j & 3] += min(__builtin_elementwise_sub_sat(keyB[j], cB1), 1u); }
;             const int cntA = wave_sum_i_dpp((int)((a4[0] + a4[1]) + (a4[2] + a4[3]))), cntB = wave_sum_i_dpp((int)((b4[0] + b4[1]) + (b4[2] + b4[3])));
;             if (!doneA) { if (cntA >= 256) prefixA = candA; if (cntA == 256) doneA = true; }
.Lsel_m7:
	s_mov_b64 s[6:7], s[0:1]
	s_lshl_b32 s0, 1, s11
	s_or_b32 s13, s0, s10
	s_or_b32 s12, s0, s33
	s_add_i32 s14, s13, -1
	s_add_i32 s15, s12, -1
	s_cmp_eq_u32 s11, 0
	s_cselect_b64 s[8:9], -1, 0
	s_add_i32 s11, s11, -1
	s_mov_b64 s[4:5], s[42:43]
	s_cmp_lt_u32 s14, 0x7fffff
	s_cselect_b32 s0, 8, 0
	v_mov_b32_e32 v2, s0
	s_cmp_lt_u32 s15, 0x7fffff
	s_cselect_b32 s0, 8, 0
	v_mov_b32_e32 v3, s0
	v_cmp_lt_u32_e64 s[0:1], s14, v127
	v_cmp_lt_u32_e64 s[100:101], s15, v81
	v_cmp_lt_u32_e32 vcc, s14, v4
	v_cndmask_b32_e64 v132, 0, 1, s[0:1]
	v_cndmask_b32_e64 v133, 0, 1, s[100:101]
	v_addc_co_u32_e32 v2, vcc, v2, v132, vcc
	v_cmp_lt_u32_e32 vcc, s15, v6
	v_cmp_lt_u32_e64 s[0:1], s14, v65
	v_cmp_lt_u32_e64 s[100:101], s15, v7
	v_addc_co_u32_e32 v3, vcc, v3, v133, vcc
	v_cmp_lt_u32_e32 vcc, s14, v129
	v_cndmask_b32_e64 v132, 0, 1, s[0:1]
	v_cndmask_b32_e64 v133, 0, 1, s[100:101]
	v_addc_co_u32_e32 v2, vcc, v2, v132, vcc
	v_cmp_lt_u32_e32 vcc, s15, v8
	v_cmp_lt_u32_e64 s[0:1], s14, v70
	v_cmp_lt_u32_e64 s[100:101], s15, v9
	v_addc_co_u32_e32 v3, vcc, v3, v133, vcc
	v_cmp_lt_u32_e32 vcc, s14, v67
	v_cndmask_b32_e64 v132, 0, 1, s[0:1]
	v_cndmask_b32_e64 v133, 0, 1, s[100:101]
	v_addc_co_u32_e32 v2, vcc, v2, v132, vcc
	v_cmp_lt_u32_e32 vcc, s15, v10
	v_cmp_lt_u32_e64 s[0:1], s14, v5
	v_cmp_lt_u32_e64 s[100:101], s15, v11
	v_addc_co_u32_e32 v3, vcc, v3, v133, vcc
	v_cmp_lt_u32_e32 vcc, s14, v69
	v_cndmask_b32_e64 v132, 0, 1, s[0:1]
	v_cndmask_b32_e64 v133, 0, 1, s[100:101]
	v_addc_co_u32_e32 v2, vcc, v2, v132, vcc
	v_cmp_lt_u32_e32 vcc, s15, v12
	v_cmp_lt_u32_e64 s[0:1], s14, v66
	v_cmp_lt_u32_e64 s[100:101], s15, v17
	v_addc_co_u32_e32 v3, vcc, v3, v133, vcc
	v_cmp_lt_u32_e32 vcc, s14, v71
	v_cndmask_b32_e64 v132, 0, 1, s[0:1]
	v_cndmask_b32_e64 v133, 0, 1, s[100:101]
	v_addc_co_u32_e32 v2, vcc, v2, v132, vcc
	v_cmp_lt_u32_e32 vcc, s15, v18
	v_cmp_lt_u32_e64 s[0:1], s14, v79
	v_cmp_lt_u32_e64 s[100:101], s15, v19
	v_addc_co_u32_e32 v3, vcc, v3, v133, vcc
	v_cmp_lt_u32_e32 vcc, s14, v72
	v_cndmask_b32_e64 v132, 0, 1, s[0:1]
	v_cndmask_b32_e64 v133, 0, 1, s[100:101]
	v_addc_co_u32_e32 v2, vcc, v2, v132, vcc
	v_cmp_lt_u32_e32 vcc, s15, v20
	v_cmp_lt_u32_e64 s[0:1], s14, v76
	v_cmp_lt_u32_e64 s[100:101], s15, v25
	v_addc_co_u32_e32 v3, vcc, v3, v133, vcc
	v_cmp_lt_u32_e32 vcc, s14, v74
	v_cndmask_b32_e64 v132, 0, 1, s[0:1]
	v_cndmask_b32_e64 v133, 0, 1, s[100:101]
	v_addc_co_u32_e32 v2, vcc, v2, v132, vcc
	v_cmp_lt_u32_e32 vcc, s15, v26
	v_cmp_lt_u32_e64 s[0:1], s14, v78
	v_cmp_lt_u32_e64 s[100:101], s15, v27
	v_addc_co_u32_e32 v3, vcc, v3, v133, vcc
	v_cmp_lt_u32_e32 vcc, s14, v92
	v_cndmask_b32_e64 v132, 0, 1, s[0:1]
	v_cndmask_b32_e64 v133, 0, 1, s[100:101]
	v_addc_co_u32_e32 v2, vcc, v2, v132, vcc
	v_cmp_lt_u32_e32 vcc, s15, v28
	v_cmp_lt_u32_e64 s[0:1], s14, v86
	v_cmp_lt_u32_e64 s[100:101], s15, v33
	v_addc_co_u32_e32 v3, vcc, v3, v133, vcc
	v_cmp_lt_u32_e32 vcc, s14, v89
	v_cndmask_b32_e64 v132, 0, 1, s[0:1]
	v_cndmask_b32_e64 v133, 0, 1, s[100:101]
	v_addc_co_u32_e32 v2, vcc, v2, v132, vcc
	v_cmp_lt_u32_e32 vcc, s15, v34
	v_cmp_lt_u32_e64 s[0:1], s14, v88
	v_cmp_lt_u32_e64 s[100:101], s15, v35
	v_addc_co_u32_e32 v3, vcc, v3, v133, vcc
	v_cmp_lt_u32_e32 vcc, s14, v91
	v_cndmask_b32_e64 v132, 0, 1, s[0:1]
	v_cndmask_b32_e64 v133, 0, 1, s[100:101]
	v_addc_co_u32_e32 v2, vcc, v2, v132, vcc
	v_cmp_lt_u32_e32 vcc, s15, v36
	v_cmp_lt_u32_e64 s[0:1], s14, v100
	v_cmp_lt_u32_e64 s[100:101], s15, v41
	v_addc_co_u32_e32 v3, vcc, v3, v133, vcc
	v_cmp_lt_u32_e32 vcc, s14, v94
	v_cndmask_b32_e64 v132, 0, 1, s[0:1]
	v_cndmask_b32_e64 v133, 0, 1, s[100:101]
	v_addc_co_u32_e32 v2, vcc, v2, v132, vcc
	v_cmp_lt_u32_e32 vcc, s15, v42
	v_cmp_lt_u32_e64 s[0:1], s14, v97
	v_cmp_lt_u32_e64 s[100:101], s15, v43
	v_addc_co_u32_e32 v3, vcc, v3, v133, vcc
	v_cmp_lt_u32_e32 vcc, s14, v96
	v_cndmask_b32_e64 v132, 0, 1, s[0:1]
	v_cndmask_b32_e64 v133, 0, 1, s[100:101]
	v_addc_co_u32_e32 v2, vcc, v2, v132, vcc
	v_cmp_lt_u32_e32 vcc, s15, v44
	v_cmp_lt_u32_e64 s[0:1], s14, v99
	v_cmp_lt_u32_e64 s[100:101], s15, v49
	v_addc_co_u32_e32 v3, vcc, v3, v133, vcc
	v_cmp_lt_u32_e32 vcc, s14, v108
	v_cndmask_b32_e64 v132, 0, 1, s[0:1]
	v_cndmask_b32_e64 v133, 0, 1, s[100:101]
	v_addc_co_u32_e32 v2, vcc, v2, v132, vcc
	v_cmp_lt_u32_e32 vcc, s15, v50
	v_cmp_lt_u32_e64 s[0:1], s14, v102
	v_cmp_lt_u32_e64 s[100:101], s15, v51
	v_addc_co_u32_e32 v3, vcc, v3, v133, vcc
	v_cmp_lt_u32_e32 vcc, s14, v105
	v_cndmask_b32_e64 v132, 0, 1, s[0:1]
	v_cndmask_b32_e64 v133, 0, 1, s[100:101]
	v_addc_co_u32_e32 v2, vcc, v2, v132, vcc
	v_cmp_lt_u32_e32 vcc, s15, v52
	v_cmp_lt_u32_e64 s[0:1], s14, v104
	v_cmp_lt_u32_e64 s[100:101], s15, v83
	v_addc_co_u32_e32 v3, vcc, v3, v133, vcc
	v_cmp_lt_u32_e32 vcc, s14, v107
	v_cndmask_b32_e64 v132, 0, 1, s[0:1]
	v_cndmask_b32_e64 v133, 0, 1, s[100:101]
	v_addc_co_u32_e32 v2, vcc, v2, v132, vcc
	v_cmp_lt_u32_e32 vcc, s15, v15
	v_cmp_lt_u32_e64 s[0:1], s14, v116
	v_cmp_lt_u32_e64 s[100:101], s15, v23
	v_addc_co_u32_e32 v3, vcc, v3, v133, vcc
	v_cmp_lt_u32_e32 vcc, s14, v110
	v_cndmask_b32_e64 v132, 0, 1, s[0:1]
	v_cndmask_b32_e64 v133, 0, 1, s[100:101]
	v_addc_co_u32_e32 v2, vcc, v2, v132, vcc
	v_cmp_lt_u32_e32 vcc, s15, v31
	v_cmp_lt_u32_e64 s[0:1], s14, v113
	v_cmp_lt_u32_e64 s[100:101], s15, v39
	v_addc_co_u32_e32 v3, vcc, v3, v133, vcc
	v_cmp_lt_u32_e32 vcc, s14, v112
	v_cndmask_b32_e64 v132, 0, 1, s[0:1]
	v_cndmask_b32_e64 v133, 0, 1, s[100:101]
	v_addc_co_u32_e32 v2, vcc, v2, v132, vcc
	v_cmp_lt_u32_e32 vcc, s15, v47
	v_cmp_lt_u32_e64 s[0:1], s14, v115
	v_cmp_lt_u32_e64 s[100:101], s15, v55
	v_addc_co_u32_e32 v3, vcc, v3, v133, vcc
	v_cmp_lt_u32_e32 vcc, s14, v128
; #define DPP_ADDI(ctrl, rmask) v += __builtin_amdgcn_update_dpp(0, v, ctrl, rmask, 0xF, false)
; __device__ __forceinline__ int wave_sum_i_dpp(int v) {
;     ...
;     DPP_ADDI(0xB1, 0xF); DPP_ADDI(0x4E, 0xF); DPP_ADDI(0x141, 0xF); DPP_ADDI(0x140, 0xF); DPP_ADDI(0x142, 0xA); DPP_ADDI(0x143, 0xC);
;     ...
;     return __builtin_amdgcn_readlane(v, 63);
; }
; __device__ __forceinline__ void select_item(const Frame& F, int l, int samp, int b, int c, int qg) {
;     ...
;             const unsigned candA = prefixA | (1u << bit), candB = prefixB | (1u << bit), cA1 = candA - 1u, cB1 = candB - 1u; unsigned a4[4] = {0u, 0u, 0u, 0u}, b4[4] = {0u, 0u, 0u, 0u};
; #pragma unroll
;             for (int j = 0; j < 64; ++j) { a4[j & 3] += min(__builtin_elementwise_sub_sat(keyA[j], cA1), 1u); b4[j & 3] += min(__builtin_elementwise_sub_sat(keyB[j], cB1), 1u); }
;             const int cntA = wave_sum_i_dpp((int)((a4[0] + a4[1]) + (a4[2] + a4[3]))), cntB = wave_sum_i_dpp((int)((b4[0] + b4[1]) + (b4[2] + b4[3])));
;             if (!doneA) { if (cntA >= 256) prefixA = candA; if (cntA == 256) doneA = true; }
;             if (!doneB) { if (cntB >= 256) prefixB = candB; if (cntB == 256) doneB = true; }
;         }
	v_cndmask_b32_e64 v132, 0, 1, s[0:1]
	v_cndmask_b32_e64 v133, 0, 1, s[100:101]
	v_addc_co_u32_e32 v2, vcc, v2, v132, vcc
	v_cmp_lt_u32_e32 vcc, s15, v82
	v_cmp_lt_u32_e64 s[0:1], s14, v75
	v_cmp_lt_u32_e64 s[100:101], s15, v16
	v_addc_co_u32_e32 v3, vcc, v3, v133, vcc
	v_cmp_lt_u32_e32 vcc, s14, v87
	v_cndmask_b32_e64 v132, 0, 1, s[0:1]
	v_cndmask_b32_e64 v133, 0, 1, s[100:101]
	v_addc_co_u32_e32 v2, vcc, v2, v132, vcc
	v_cmp_lt_u32_e32 vcc, s15, v24
	v_cmp_lt_u32_e64 s[0:1], s14, v95
	v_cmp_lt_u32_e64 s[100:101], s15, v32
	v_addc_co_u32_e32 v3, vcc, v3, v133, vcc
	v_cmp_lt_u32_e32 vcc, s14, v103
	v_cndmask_b32_e64 v132, 0, 1, s[0:1]
	v_cndmask_b32_e64 v133, 0, 1, s[100:101]
	v_addc_co_u32_e32 v2, vcc, v2, v132, vcc
	v_cmp_lt_u32_e32 vcc, s15, v40
	v_cmp_lt_u32_e64 s[0:1], s14, v111
	v_cmp_lt_u32_e64 s[100:101], s15, v48
	v_addc_co_u32_e32 v3, vcc, v3, v133, vcc
	v_cmp_lt_u32_e32 vcc, s14, v119
	v_cndmask_b32_e64 v132, 0, 1, s[0:1]
	v_cndmask_b32_e64 v133, 0, 1, s[100:101]
	v_addc_co_u32_e32 v2, vcc, v2, v132, vcc
	v_cmp_lt_u32_e32 vcc, s15, v56
	v_cmp_lt_u32_e64 s[0:1], s14, v131
	v_cmp_lt_u32_e64 s[100:101], s15, v85
	v_addc_co_u32_e32 v3, vcc, v3, v133, vcc
	v_cmp_lt_u32_e32 vcc, s14, v68
	v_cndmask_b32_e64 v132, 0, 1, s[0:1]
	v_cndmask_b32_e64 v133, 0, 1, s[100:101]
	v_addc_co_u32_e32 v2, vcc, v2, v132, vcc
	v_cmp_lt_u32_e32 vcc, s15, v13
	v_cmp_lt_u32_e64 s[0:1], s14, v77
	v_cmp_lt_u32_e64 s[100:101], s15, v21
	v_addc_co_u32_e32 v3, vcc, v3, v133, vcc
	v_cmp_lt_u32_e32 vcc, s14, v90
	v_cndmask_b32_e64 v132, 0, 1, s[0:1]
	v_cndmask_b32_e64 v133, 0, 1, s[100:101]
	v_addc_co_u32_e32 v2, vcc, v2, v132, vcc
	v_cmp_lt_u32_e32 vcc, s15, v29
	v_cmp_lt_u32_e64 s[0:1], s14, v98
	v_cmp_lt_u32_e64 s[100:101], s15, v37
	v_addc_co_u32_e32 v3, vcc, v3, v133, vcc
	v_cmp_lt_u32_e32 vcc, s14, v106
	v_cndmask_b32_e64 v132, 0, 1, s[0:1]
	v_cndmask_b32_e64 v133, 0, 1, s[100:101]
	v_addc_co_u32_e32 v2, vcc, v2, v132, vcc
	v_cmp_lt_u32_e32 vcc, s15, v45
	v_cmp_lt_u32_e64 s[0:1], s14, v114
	v_cmp_lt_u32_e64 s[100:101], s15, v53
	v_addc_co_u32_e32 v3, vcc, v3, v133, vcc
	v_cmp_lt_u32_e32 vcc, s14, v130
	v_cndmask_b32_e64 v132, 0, 1, s[0:1]
	v_cndmask_b32_e64 v133, 0, 1, s[100:101]
	v_addc_co_u32_e32 v2, vcc, v2, v132, vcc
	v_cmp_lt_u32_e32 vcc, s15, v84
	v_cmp_lt_u32_e64 s[0:1], s14, v73
	v_cmp_lt_u32_e64 s[100:101], s15, v14
	v_addc_co_u32_e32 v3, vcc, v3, v133, vcc
	v_cmp_lt_u32_e32 vcc, s14, v80
	v_cndmask_b32_e64 v132, 0, 1, s[0:1]
	v_cndmask_b32_e64 v133, 0, 1, s[100:101]
	v_addc_co_u32_e32 v2, vcc, v2, v132, vcc
	v_cmp_lt_u32_e32 vcc, s15, v22
	v_cmp_lt_u32_e64 s[0:1], s14, v93
	v_cmp_lt_u32_e64 s[100:101], s15, v30
	v_addc_co_u32_e32 v3, vcc, v3, v133, vcc
	v_cmp_lt_u32_e32 vcc, s14, v101
	v_cndmask_b32_e64 v132, 0, 1, s[0:1]
	v_cndmask_b32_e64 v133, 0, 1, s[100:101]
	v_addc_co_u32_e32 v2, vcc, v2, v132, vcc
	v_cmp_lt_u32_e32 vcc, s15, v38
	v_cmp_lt_u32_e64 s[0:1], s14, v109
	v_cmp_lt_u32_e64 s[100:101], s15, v46
	v_addc_co_u32_e32 v3, vcc, v3, v133, vcc
	v_cmp_lt_u32_e32 vcc, s14, v117
	v_cndmask_b32_e64 v132, 0, 1, s[0:1]
	v_cndmask_b32_e64 v133, 0, 1, s[100:101]
	v_addc_co_u32_e32 v2, vcc, v2, v132, vcc
	v_cmp_lt_u32_e32 vcc, s15, v54
	s_nop 1
	v_addc_co_u32_e32 v3, vcc, v3, v133, vcc
	v_lshl_add_u32 v2, v3, 16, v2
	s_nop 1
	v_add_u32_dpp v2, v2, v2 quad_perm:[1,0,3,2] row_mask:0xf bank_mask:0xf bound_ctrl:1
	s_nop 1
	v_add_u32_dpp v2, v2, v2 quad_perm:[2,3,0,1] row_mask:0xf bank_mask:0xf bound_ctrl:1
	s_nop 1
	v_add_u32_dpp v2, v2, v2 row_half_mirror row_mask:0xf bank_mask:0xf bound_ctrl:1
	s_nop 1
	v_add_u32_dpp v2, v2, v2 row_mirror row_mask:0xf bank_mask:0xf bound_ctrl:1
	s_nop 1
	v_add_u32_dpp v2, v2, v2 row_bcast:15 row_mask:0xa bank_mask:0xf
	s_nop 1
	v_add_u32_dpp v2, v2, v2 row_bcast:31 row_mask:0xc bank_mask:0xf
	s_nop 0
	v_readlane_b32 s0, v2, 63
	s_lshr_b32 s14, s0, 16
	s_and_b32 s0, s0, 0xffff
	s_cmpk_gt_i32 s0, 0xff
	s_cselect_b32 s13, s13, s10
	s_cmpk_eq_i32 s0, 0x100
	s_cselect_b64 s[0:1], -1, 0
	s_or_b64 s[0:1], s[6:7], s[0:1]
	s_and_b64 s[6:7], s[6:7], exec
	s_cselect_b32 s10, s10, s13
	s_cmpk_gt_i32 s14, 0xff
	s_cselect_b32 s12, s12, s33
	s_cmpk_eq_i32 s14, 0x100
	s_cselect_b64 s[6:7], -1, 0
	s_or_b64 s[42:43], s[42:43], s[6:7]
	s_and_b64 s[4:5], s[4:5], exec
	s_cselect_b32 s33, s33, s12
	s_and_b64 s[4:5], s[0:1], s[42:43]
	s_or_b64 s[4:5], s[8:9], s[4:5]
	s_and_b64 vcc, exec, s[4:5]
	s_cbranch_vccz .Lsel_m7
	s_branch .Lsel_exit
; __device__ __forceinline__ void select_item(const Frame& F, int l, int samp, int b, int c, int qg) {
;     ...
;             const unsigned candA = prefixA | (1u << bit), candB = prefixB | (1u << bit), cA1 = candA - 1u, cB1 = candB - 1u; unsigned a4[4] = {0u, 0u, 0u, 0u}, b4[4] = {0u, 0u, 0u, 0u};
; #pragma unroll
;             for (int j = 0; j < 64; ++j) { a4[j & 3] += min(__builtin_elementwise_sub_sat(keyA[j], cA1), 1u); b4[j & 3] += min(__builtin_elementwise_sub_sat(keyB[j], cB1), 1u); }
;             const int cntA = wave_sum_i_dpp((int)((a4[0] + a4[1]) + (a4[2] + a4[3]))), cntB = wave_sum_i_dpp((int)((b4[0] + b4[1]) + (b4[2] + b4[3])));
;             if (!doneA) { if (cntA >= 256) prefixA = candA; if (cntA == 256) doneA = true; }
.Lsel_m8:
	s_mov_b64 s[6:7], s[0:1]
	s_lshl_b32 s0, 1, s11
	s_or_b32 s13, s0, s10
	s_or_b32 s12, s0, s33
	s_add_i32 s14, s13, -1
	s_add_i32 s15, s12, -1
	s_cmp_eq_u32 s11, 0
	s_cselect_b64 s[8:9], -1, 0
	s_add_i32 s11, s11, -1
	s_mov_b64 s[4:5], s[42:43]
	s_cmp_lt_u32 s14, 0x7fffff
	s_cselect_b32 s0, 0, 0
	v_mov_b32_e32 v2, s0
	s_cmp_lt_u32 s15, 0x7fffff
	s_cselect_b32 s0, 0, 0
	v_mov_b32_e32 v3, s0
	v_cmp_lt_u32_e64 s[0:1], s14, v127
	v_cmp_lt_u32_e64 s[100:101], s15, v81
	v_cmp_lt_u32_e32 vcc, s14, v4
	v_cndmask_b32_e64 v132, 0, 1, s[0:1]
	v_cndmask_b32_e64 v133, 0, 1, s[100:101]
	v_addc_co_u32_e32 v2, vcc, v2, v132, vcc
	v_cmp_lt_u32_e32 vcc, s15, v6
	v_cmp_lt_u32_e64 s[0:1], s14, v65
	v_cmp_lt_u32_e64 s[100:101], s15, v7
	v_addc_co_u32_e32 v3, vcc, v3, v133, vcc
	v_cmp_lt_u32_e32 vcc, s14, v129
	v_cndmask_b32_e64 v132, 0, 1, s[0:1]
	v_cndmask_b32_e64 v133, 0, 1, s[100:101]
	v_addc_co_u32_e32 v2, vcc, v2, v132, vcc
	v_cmp_lt_u32_e32 vcc, s15, v8
	v_cmp_lt_u32_e64 s[0:1], s14, v70
	v_cmp_lt_u32_e64 s[100:101], s15, v9
	v_addc_co_u32_e32 v3, vcc, v3, v133, vcc
	v_cmp_lt_u32_e32 vcc, s14, v67
	v_cndmask_b32_e64 v132, 0, 1, s[0:1]
	v_cndmask_b32_e64 v133, 0, 1, s[100:101]
	v_addc_co_u32_e32 v2, vcc, v2, v132, vcc
	v_cmp_lt_u32_e32 vcc, s15, v10
	v_cmp_lt_u32_e64 s[0:1], s14, v5
	v_cmp_lt_u32_e64 s[100:101], s15, v11
	v_addc_co_u32_e32 v3, vcc, v3, v133, vcc
	v_cmp_lt_u32_e32 vcc, s14, v69
	v_cndmask_b32_e64 v132, 0, 1, s[0:1]
	v_cndmask_b32_e64 v133, 0, 1, s[100:101]
	v_addc_co_u32_e32 v2, vcc, v2, v132, vcc
	v_cmp_lt_u32_e32 vcc, s15, v12
	v_cmp_lt_u32_e64 s[0:1], s14, v66
	v_cmp_lt_u32_e64 s[100:101], s15, v17
	v_addc_co_u32_e32 v3, vcc, v3, v133, vcc
	v_cmp_lt_u32_e32 vcc, s14, v71
	v_cndmask_b32_e64 v132, 0, 1, s[0:1]
	v_cndmask_b32_e64 v133, 0, 1, s[100:101]
	v_addc_co_u32_e32 v2, vcc, v2, v132, vcc
	v_cmp_lt_u32_e32 vcc, s15, v18
	v_cmp_lt_u32_e64 s[0:1], s14, v79
	v_cmp_lt_u32_e64 s[100:101], s15, v19
	v_addc_co_u32_e32 v3, vcc, v3, v133, vcc
	v_cmp_lt_u32_e32 vcc, s14, v72
	v_cndmask_b32_e64 v132, 0, 1, s[0:1]
	v_cndmask_b32_e64 v133, 0, 1, s[100:101]
	v_addc_co_u32_e32 v2, vcc, v2, v132, vcc
	v_cmp_lt_u32_e32 vcc, s15, v20
	v_cmp_lt_u32_e64 s[0:1], s14, v76
	v_cmp_lt_u32_e64 s[100:101], s15, v25
	v_addc_co_u32_e32 v3, vcc, v3, v133, vcc
	v_cmp_lt_u32_e32 vcc, s14, v74
	v_cndmask_b32_e64 v132, 0, 1, s[0:1]
	v_cndmask_b32_e64 v133, 0, 1, s[100:101]
	v_addc_co_u32_e32 v2, vcc, v2, v132, vcc
	v_cmp_lt_u32_e32 vcc, s15, v26
	v_cmp_lt_u32_e64 s[0:1], s14, v78
	v_cmp_lt_u32_e64 s[100:101], s15, v27
	v_addc_co_u32_e32 v3, vcc, v3, v133, vcc
	v_cmp_lt_u32_e32 vcc, s14, v92
	v_cndmask_b32_e64 v132, 0, 1, s[0:1]
	v_cndmask_b32_e64 v133, 0, 1, s[100:101]
	v_addc_co_u32_e32 v2, vcc, v2, v132, vcc
	v_cmp_lt_u32_e32 vcc, s15, v28
	v_cmp_lt_u32_e64 s[0:1], s14, v86
	v_cmp_lt_u32_e64 s[100:101], s15, v33
	v_addc_co_u32_e32 v3, vcc, v3, v133, vcc
	v_cmp_lt_u32_e32 vcc, s14, v89
	v_cndmask_b32_e64 v132, 0, 1, s[0:1]
	v_cndmask_b32_e64 v133, 0, 1, s[100:101]
	v_addc_co_u32_e32 v2, vcc, v2, v132, vcc
	v_cmp_lt_u32_e32 vcc, s15, v34
	v_cmp_lt_u32_e64 s[0:1], s14, v88
	v_cmp_lt_u32_e64 s[100:101], s15, v35
	v_addc_co_u32_e32 v3, vcc, v3, v133, vcc
	v_cmp_lt_u32_e32 vcc, s14, v91
	v_cndmask_b32_e64 v132, 0, 1, s[0:1]
	v_cndmask_b32_e64 v133, 0, 1, s[100:101]
	v_addc_co_u32_e32 v2, vcc, v2, v132, vcc
	v_cmp_lt_u32_e32 vcc, s15, v36
	v_cmp_lt_u32_e64 s[0:1], s14, v100
	v_cmp_lt_u32_e64 s[100:101], s15, v41
	v_addc_co_u32_e32 v3, vcc, v3, v133, vcc
	v_cmp_lt_u32_e32 vcc, s14, v94
	v_cndmask_b32_e64 v132, 0, 1, s[0:1]
	v_cndmask_b32_e64 v133, 0, 1, s[100:101]
	v_addc_co_u32_e32 v2, vcc, v2, v132, vcc
	v_cmp_lt_u32_e32 vcc, s15, v42
	v_cmp_lt_u32_e64 s[0:1], s14, v97
	v_cmp_lt_u32_e64 s[100:101], s15, v43
	v_addc_co_u32_e32 v3, vcc, v3, v133, vcc
	v_cmp_lt_u32_e32 vcc, s14, v96
	v_cndmask_b32_e64 v132, 0, 1, s[0:1]
	v_cndmask_b32_e64 v133, 0, 1, s[100:101]
	v_addc_co_u32_e32 v2, vcc, v2, v132, vcc
	v_cmp_lt_u32_e32 vcc, s15, v44
	v_cmp_lt_u32_e64 s[0:1], s14, v99
	v_cmp_lt_u32_e64 s[100:101], s15, v49
	v_addc_co_u32_e32 v3, vcc, v3, v133, vcc
	v_cmp_lt_u32_e32 vcc, s14, v108
	v_cndmask_b32_e64 v132, 0, 1, s[0:1]
	v_cndmask_b32_e64 v133, 0, 1, s[100:101]
	v_addc_co_u32_e32 v2, vcc, v2, v132, vcc
	v_cmp_lt_u32_e32 vcc, s15, v50
	v_cmp_lt_u32_e64 s[0:1], s14, v102
	v_cmp_lt_u32_e64 s[100:101], s15, v51
	v_addc_co_u32_e32 v3, vcc, v3, v133, vcc
	v_cmp_lt_u32_e32 vcc, s14, v105
	v_cndmask_b32_e64 v132, 0, 1, s[0:1]
	v_cndmask_b32_e64 v133, 0, 1, s[100:101]
	v_addc_co_u32_e32 v2, vcc, v2, v132, vcc
	v_cmp_lt_u32_e32 vcc, s15, v52
	v_cmp_lt_u32_e64 s[0:1], s14, v104
	v_cmp_lt_u32_e64 s[100:101], s15, v57
	v_addc_co_u32_e32 v3, vcc, v3, v133, vcc
	v_cmp_lt_u32_e32 vcc, s14, v107
	v_cndmask_b32_e64 v132, 0, 1, s[0:1]
	v_cndmask_b32_e64 v133, 0, 1, s[100:101]
	v_addc_co_u32_e32 v2, vcc, v2, v132, vcc
	v_cmp_lt_u32_e32 vcc, s15, v58
	v_cmp_lt_u32_e64 s[0:1], s14, v116
	v_cmp_lt_u32_e64 s[100:101], s15, v59
	v_addc_co_u32_e32 v3, vcc, v3, v133, vcc
	v_cmp_lt_u32_e32 vcc, s14, v110
	v_cndmask_b32_e64 v132, 0, 1, s[0:1]
	v_cndmask_b32_e64 v133, 0, 1, s[100:101]
	v_addc_co_u32_e32 v2, vcc, v2, v132, vcc
	v_cmp_lt_u32_e32 vcc, s15, v60
	v_cmp_lt_u32_e64 s[0:1], s14, v113
	v_cmp_lt_u32_e64 s[100:101], s15, v83
	v_addc_co_u32_e32 v3, vcc, v3, v133, vcc
	v_cmp_lt_u32_e32 vcc, s14, v112
	v_cndmask_b32_e64 v132, 0, 1, s[0:1]
	v_cndmask_b32_e64 v133, 0, 1, s[100:101]
	v_addc_co_u32_e32 v2, vcc, v2, v132, vcc
	v_cmp_lt_u32_e32 vcc, s15, v15
	v_cmp_lt_u32_e64 s[0:1], s14, v115
	v_cmp_lt_u32_e64 s[100:101], s15, v23
	v_addc_co_u32_e32 v3, vcc, v3, v133, vcc
	v_cmp_lt_u32_e32 vcc, s14, v124
; #define DPP_ADDI(ctrl, rmask) v += __builtin_amdgcn_update_dpp(0, v, ctrl, rmask, 0xF, false)
; __device__ __forceinline__ int wave_sum_i_dpp(int v) {
;     ...
;     DPP_ADDI(0xB1, 0xF); DPP_ADDI(0x4E, 0xF); DPP_ADDI(0x141, 0xF); DPP_ADDI(0x140, 0xF); DPP_ADDI(0x142, 0xA); DPP_ADDI(0x143, 0xC);
;     ...
;     return __builtin_amdgcn_readlane(v, 63);
; }
; __device__ __forceinline__ void select_item(const Frame& F, int l, int samp, int b, int c, int qg) {
;     ...
;             const unsigned candA = prefixA | (1u << bit), candB = prefixB | (1u << bit), cA1 = candA - 1u, cB1 = candB - 1u; unsigned a4[4] = {0u, 0u, 0u, 0u}, b4[4] = {0u, 0u, 0u, 0u};
; #pragma unroll
;             for (int j = 0; j < 64; ++j) { a4[j & 3] += min(__builtin_elementwise_sub_sat(keyA[j], cA1), 1u); b4[j & 3] += min(__builtin_elementwise_sub_sat(keyB[j], cB1), 1u); }
;             const int cntA = wave_sum_i_dpp((int)((a4[0] + a4[1]) + (a4[2] + a4[3]))), cntB = wave_sum_i_dpp((int)((b4[0] + b4[1]) + (b4[2] + b4[3])));
;             if (!doneA) { if (cntA >= 256) prefixA = candA; if (cntA == 256) doneA = true; }
;             if (!doneB) { if (cntB >= 256) prefixB = candB; if (cntB == 256) doneB = true; }
;         }
	v_cndmask_b32_e64 v132, 0, 1, s[0:1]
	v_cndmask_b32_e64 v133, 0, 1, s[100:101]
	v_addc_co_u32_e32 v2, vcc, v2, v132, vcc
	v_cmp_lt_u32_e32 vcc, s15, v31
	v_cmp_lt_u32_e64 s[0:1], s14, v118
	v_cmp_lt_u32_e64 s[100:101], s15, v39
	v_addc_co_u32_e32 v3, vcc, v3, v133, vcc
	v_cmp_lt_u32_e32 vcc, s14, v121
	v_cndmask_b32_e64 v132, 0, 1, s[0:1]
	v_cndmask_b32_e64 v133, 0, 1, s[100:101]
	v_addc_co_u32_e32 v2, vcc, v2, v132, vcc
	v_cmp_lt_u32_e32 vcc, s15, v47
	v_cmp_lt_u32_e64 s[0:1], s14, v120
	v_cmp_lt_u32_e64 s[100:101], s15, v55
	v_addc_co_u32_e32 v3, vcc, v3, v133, vcc
	v_cmp_lt_u32_e32 vcc, s14, v123
	v_cndmask_b32_e64 v132, 0, 1, s[0:1]
	v_cndmask_b32_e64 v133, 0, 1, s[100:101]
	v_addc_co_u32_e32 v2, vcc, v2, v132, vcc
	v_cmp_lt_u32_e32 vcc, s15, v63
	v_cmp_lt_u32_e64 s[0:1], s14, v128
	v_cmp_lt_u32_e64 s[100:101], s15, v82
	v_addc_co_u32_e32 v3, vcc, v3, v133, vcc
	v_cmp_lt_u32_e32 vcc, s14, v75
	v_cndmask_b32_e64 v132, 0, 1, s[0:1]
	v_cndmask_b32_e64 v133, 0, 1, s[100:101]
	v_addc_co_u32_e32 v2, vcc, v2, v132, vcc
	v_cmp_lt_u32_e32 vcc, s15, v16
	v_cmp_lt_u32_e64 s[0:1], s14, v87
	v_cmp_lt_u32_e64 s[100:101], s15, v24
	v_addc_co_u32_e32 v3, vcc, v3, v133, vcc
	v_cmp_lt_u32_e32 vcc, s14, v95
	v_cndmask_b32_e64 v132, 0, 1, s[0:1]
	v_cndmask_b32_e64 v133, 0, 1, s[100:101]
	v_addc_co_u32_e32 v2, vcc, v2, v132, vcc
	v_cmp_lt_u32_e32 vcc, s15, v32
	v_cmp_lt_u32_e64 s[0:1], s14, v103
	v_cmp_lt_u32_e64 s[100:101], s15, v40
	v_addc_co_u32_e32 v3, vcc, v3, v133, vcc
	v_cmp_lt_u32_e32 vcc, s14, v111
	v_cndmask_b32_e64 v132, 0, 1, s[0:1]
	v_cndmask_b32_e64 v133, 0, 1, s[100:101]
	v_addc_co_u32_e32 v2, vcc, v2, v132, vcc
	v_cmp_lt_u32_e32 vcc, s15, v48
	v_cmp_lt_u32_e64 s[0:1], s14, v119
	v_cmp_lt_u32_e64 s[100:101], s15, v56
	v_addc_co_u32_e32 v3, vcc, v3, v133, vcc
	v_cmp_lt_u32_e32 vcc, s14, v126
	v_cndmask_b32_e64 v132, 0, 1, s[0:1]
	v_cndmask_b32_e64 v133, 0, 1, s[100:101]
	v_addc_co_u32_e32 v2, vcc, v2, v132, vcc
	v_cmp_lt_u32_e32 vcc, s15, v64
	v_cmp_lt_u32_e64 s[0:1], s14, v131
	v_cmp_lt_u32_e64 s[100:101], s15, v85
	v_addc_co_u32_e32 v3, vcc, v3, v133, vcc
	v_cmp_lt_u32_e32 vcc, s14, v68
	v_cndmask_b32_e64 v132, 0, 1, s[0:1]
	v_cndmask_b32_e64 v133, 0, 1, s[100:101]
	v_addc_co_u32_e32 v2, vcc, v2, v132, vcc
	v_cmp_lt_u32_e32 vcc, s15, v13
	v_cmp_lt_u32_e64 s[0:1], s14, v77
	v_cmp_lt_u32_e64 s[100:101], s15, v21
	v_addc_co_u32_e32 v3, vcc, v3, v133, vcc
	v_cmp_lt_u32_e32 vcc, s14, v90
	v_cndmask_b32_e64 v132, 0, 1, s[0:1]
	v_cndmask_b32_e64 v133, 0, 1, s[100:101]
	v_addc_co_u32_e32 v2, vcc, v2, v132, vcc
	v_cmp_lt_u32_e32 vcc, s15, v29
	v_cmp_lt_u32_e64 s[0:1], s14, v98
	v_cmp_lt_u32_e64 s[100:101], s15, v37
	v_addc_co_u32_e32 v3, vcc, v3, v133, vcc
	v_cmp_lt_u32_e32 vcc, s14, v106
	v_cndmask_b32_e64 v132, 0, 1, s[0:1]
	v_cndmask_b32_e64 v133, 0, 1, s[100:101]
	v_addc_co_u32_e32 v2, vcc, v2, v132, vcc
	v_cmp_lt_u32_e32 vcc, s15, v45
	v_cmp_lt_u32_e64 s[0:1], s14, v114
	v_cmp_lt_u32_e64 s[100:101], s15, v53
	v_addc_co_u32_e32 v3, vcc, v3, v133, vcc
	v_cmp_lt_u32_e32 vcc, s14, v122
	v_cndmask_b32_e64 v132, 0, 1, s[0:1]
	v_cndmask_b32_e64 v133, 0, 1, s[100:101]
	v_addc_co_u32_e32 v2, vcc, v2, v132, vcc
	v_cmp_lt_u32_e32 vcc, s15, v61
	v_cmp_lt_u32_e64 s[0:1], s14, v130
	v_cmp_lt_u32_e64 s[100:101], s15, v84
	v_addc_co_u32_e32 v3, vcc, v3, v133, vcc
	v_cmp_lt_u32_e32 vcc, s14, v73
	v_cndmask_b32_e64 v132, 0, 1, s[0:1]
	v_cndmask_b32_e64 v133, 0, 1, s[100:101]
	v_addc_co_u32_e32 v2, vcc, v2, v132, vcc
	v_cmp_lt_u32_e32 vcc, s15, v14
	v_cmp_lt_u32_e64 s[0:1], s14, v80
	v_cmp_lt_u32_e64 s[100:101], s15, v22
	v_addc_co_u32_e32 v3, vcc, v3, v133, vcc
	v_cmp_lt_u32_e32 vcc, s14, v93
	v_cndmask_b32_e64 v132, 0, 1, s[0:1]
	v_cndmask_b32_e64 v133, 0, 1, s[100:101]
	v_addc_co_u32_e32 v2, vcc, v2, v132, vcc
	v_cmp_lt_u32_e32 vcc, s15, v30
	v_cmp_lt_u32_e64 s[0:1], s14, v101
	v_cmp_lt_u32_e64 s[100:101], s15, v38
	v_addc_co_u32_e32 v3, vcc, v3, v133, vcc
	v_cmp_lt_u32_e32 vcc, s14, v109
	v_cndmask_b32_e64 v132, 0, 1, s[0:1]
	v_cndmask_b32_e64 v133, 0, 1, s[100:101]
	v_addc_co_u32_e32 v2, vcc, v2, v132, vcc
	v_cmp_lt_u32_e32 vcc, s15, v46
	v_cmp_lt_u32_e64 s[0:1], s14, v117
	v_cmp_lt_u32_e64 s[100:101], s15, v54
	v_addc_co_u32_e32 v3, vcc, v3, v133, vcc
	v_cmp_lt_u32_e32 vcc, s14, v125
	v_cndmask_b32_e64 v132, 0, 1, s[0:1]
	v_cndmask_b32_e64 v133, 0, 1, s[100:101]
	v_addc_co_u32_e32 v2, vcc, v2, v132, vcc
	v_cmp_lt_u32_e32 vcc, s15, v62
	s_nop 1
	v_addc_co_u32_e32 v3, vcc, v3, v133, vcc
	v_lshl_add_u32 v2, v3, 16, v2
	s_nop 1
	v_add_u32_dpp v2, v2, v2 quad_perm:[1,0,3,2] row_mask:0xf bank_mask:0xf bound_ctrl:1
	s_nop 1
	v_add_u32_dpp v2, v2, v2 quad_perm:[2,3,0,1] row_mask:0xf bank_mask:0xf bound_ctrl:1
	s_nop 1
	v_add_u32_dpp v2, v2, v2 row_half_mirror row_mask:0xf bank_mask:0xf bound_ctrl:1
	s_nop 1
	v_add_u32_dpp v2, v2, v2 row_mirror row_mask:0xf bank_mask:0xf bound_ctrl:1
	s_nop 1
	v_add_u32_dpp v2, v2, v2 row_bcast:15 row_mask:0xa bank_mask:0xf
	s_nop 1
	v_add_u32_dpp v2, v2, v2 row_bcast:31 row_mask:0xc bank_mask:0xf
	s_nop 0
	v_readlane_b32 s0, v2, 63
	s_lshr_b32 s14, s0, 16
	s_and_b32 s0, s0, 0xffff
	s_cmpk_gt_i32 s0, 0xff
	s_cselect_b32 s13, s13, s10
	s_cmpk_eq_i32 s0, 0x100
	s_cselect_b64 s[0:1], -1, 0
	s_or_b64 s[0:1], s[6:7], s[0:1]
	s_and_b64 s[6:7], s[6:7], exec
	s_cselect_b32 s10, s10, s13
	s_cmpk_gt_i32 s14, 0xff
	s_cselect_b32 s12, s12, s33
	s_cmpk_eq_i32 s14, 0x100
	s_cselect_b64 s[6:7], -1, 0
	s_or_b64 s[42:43], s[42:43], s[6:7]
	s_and_b64 s[4:5], s[4:5], exec
	s_cselect_b32 s33, s33, s12
	s_and_b64 s[4:5], s[0:1], s[42:43]
	s_or_b64 s[4:5], s[8:9], s[4:5]
	s_and_b64 vcc, exec, s[4:5]
	s_cbranch_vccz .Lsel_m8
	s_branch .Lsel_exit
.Lsel_disp:
	s_cmp_eq_u32 s98, 0
	s_cbranch_scc1 .Lsel_m1
	s_cmp_eq_u32 s98, 1
	s_cbranch_scc1 .Lsel_m2
	s_cmp_eq_u32 s98, 2
	s_cbranch_scc1 .Lsel_m3
	s_cmp_eq_u32 s98, 3
	s_cbranch_scc1 .Lsel_m4
	s_cmp_eq_u32 s98, 4
	s_cbranch_scc1 .Lsel_m5
	s_cmp_eq_u32 s98, 5
	s_cbranch_scc1 .Lsel_m6
	s_cmp_eq_u32 s98, 6
	s_cbranch_scc1 .Lsel_m7
	s_cmp_eq_u32 s98, 7
	s_cbranch_scc1 .Lsel_m8
